# unit start no longer drains the previous epilogue's stores: Win peel-top and residual-GEMM pre-peel vmcnt(0) replaced by counted waits in the first load segment
# speedup vs baseline: 1.0034x; 1.0014x over previous
.LBB0_633:
	s_ashr_i32 s13, s12, 31
	s_lshl_b64 s[14:15], s[12:13], 19
	s_add_u32 s14, s37, s14
	s_addc_u32 s15, s42, s15
	s_and_b64 s[16:17], s[4:5], exec
	s_cselect_b32 s13, s15, s23
	s_cselect_b32 s19, s14, s22
	s_ashr_i32 s11, s10, 31
	s_lshl_b64 s[16:17], s[10:11], 19
	s_add_u32 s16, s29, s16
	s_addc_u32 s17, s43, s17
	s_and_b64 s[24:25], s[4:5], exec
	s_cselect_b32 s11, s17, s21
	s_cselect_b32 s60, s16, s20
	s_add_u32 s61, s20, 0x100
	s_addc_u32 s62, s21, 0
	s_add_u32 s20, s22, 0x40080
	s_addc_u32 s21, s23, 0
	s_mov_b32 s63, -2
	s_add_u32 s22, s20, 0xfffc0080
	s_addc_u32 s23, s21, -1
	s_add_i32 s64, 0, 0x10000
	s_cmp_eq_u32 s63, 12
	s_cselect_b32 s25, s13, s23
	s_cselect_b32 s24, s19, s22
	s_cselect_b32 s23, s11, s62
	s_cselect_b32 s22, s60, s61
	s_add_i32 s68, 0, 0x14000
	s_waitcnt lgkmcnt(0)
	s_lshl_b32 s74, s18, 8
	v_add_u32_e32 v178, s74, v182
	v_ashrrev_i32_e32 v179, 31, v178
	v_lshlrev_b64 v[178:179], 6, v[178:179]
	v_lshl_add_u64 v[178:179], s[70:71], 0, v[178:179]
	s_and_saveexec_b64 s[78:79], s[2:3]
	global_load_dwordx4 v[238:241], v[178:179], off
	global_load_dwordx4 v[242:245], v[178:179], off offset:16
	global_load_dwordx4 v[246:249], v[178:179], off offset:32
	global_load_dwordx4 v[250:253], v[178:179], off offset:48
	s_mov_b64 exec, s[78:79]
	v_add_u32_e32 v140, s64, v175
	v_add_u32_e32 v170, s68, v175
	ds_read_b128 v[128:131], v140
	ds_read_b128 v[132:135], v140 offset:1024
	ds_read_b128 v[136:139], v140 offset:2048
	ds_read_b128 v[140:143], v140 offset:3072
	ds_read_b128 v[144:147], v170
	ds_read_b128 v[162:165], v170 offset:1024
	ds_read_b128 v[166:169], v170 offset:2048
	ds_read_b128 v[170:173], v170 offset:3072
	v_lshl_add_u64 v[220:221], s[20:21], 0, v[160:161]
	s_add_i32 m0, s50, 0xc000
	ds_read_b128 v[186:189], v185
	ds_read_b128 v[190:193], v185 offset:1024
	ds_read_b128 v[194:197], v185 offset:2048
	ds_read_b128 v[198:201], v185 offset:3072
	ds_read_b128 v[202:205], v185 offset:4096
	ds_read_b128 v[206:209], v185 offset:5120
	ds_read_b128 v[210:213], v185 offset:6144
	ds_read_b128 v[228:231], v185 offset:7168
	global_load_lds_dwordx4 v[220:221], off
	v_lshl_add_u64 v[220:221], s[20:21], 0, v[158:159]
	s_add_i32 m0, s50, 0xe000
	s_nop 0
	global_load_lds_dwordx4 v[220:221], off
	s_waitcnt vmcnt(16)
	s_waitcnt lgkmcnt(0)
	s_barrier
	s_setprio 1
	v_mfma_f32_16x16x32_bf16 v[124:127], v[128:131], v[186:189], 0
	v_mfma_f32_16x16x32_bf16 v[120:123], v[136:139], v[186:189], 0
	v_mfma_f32_16x16x32_bf16 v[108:111], v[128:131], v[194:197], 0
	v_mfma_f32_16x16x32_bf16 v[104:107], v[136:139], v[194:197], 0
	v_mfma_f32_16x16x32_bf16 v[92:95], v[128:131], v[202:205], 0
	v_mfma_f32_16x16x32_bf16 v[88:91], v[136:139], v[202:205], 0
	v_mfma_f32_16x16x32_bf16 v[76:79], v[128:131], v[210:213], 0
	v_mfma_f32_16x16x32_bf16 v[72:75], v[136:139], v[210:213], 0
	v_mfma_f32_16x16x32_bf16 v[124:127], v[132:135], v[190:193], v[124:127]
	v_mfma_f32_16x16x32_bf16 v[120:123], v[140:143], v[190:193], v[120:123]
	v_mfma_f32_16x16x32_bf16 v[108:111], v[132:135], v[198:201], v[108:111]
	v_mfma_f32_16x16x32_bf16 v[104:107], v[140:143], v[198:201], v[104:107]
	v_mfma_f32_16x16x32_bf16 v[92:95], v[132:135], v[206:209], v[92:95]
	v_mfma_f32_16x16x32_bf16 v[88:91], v[140:143], v[206:209], v[88:91]
	v_mfma_f32_16x16x32_bf16 v[76:79], v[132:135], v[228:231], v[76:79]
	v_mfma_f32_16x16x32_bf16 v[72:75], v[140:143], v[228:231], v[72:75]
	v_mfma_f32_16x16x32_bf16 v[116:119], v[144:147], v[186:189], 0
	v_mfma_f32_16x16x32_bf16 v[112:115], v[166:169], v[186:189], 0
	v_mfma_f32_16x16x32_bf16 v[100:103], v[144:147], v[194:197], 0
	v_mfma_f32_16x16x32_bf16 v[96:99], v[166:169], v[194:197], 0
	v_mfma_f32_16x16x32_bf16 v[84:87], v[144:147], v[202:205], 0
	v_mfma_f32_16x16x32_bf16 v[80:83], v[166:169], v[202:205], 0
	v_mfma_f32_16x16x32_bf16 v[68:71], v[144:147], v[210:213], 0
	v_mfma_f32_16x16x32_bf16 v[64:67], v[166:169], v[210:213], 0
	v_mfma_f32_16x16x32_bf16 v[116:119], v[162:165], v[190:193], v[116:119]
	v_mfma_f32_16x16x32_bf16 v[112:115], v[170:173], v[190:193], v[112:115]
	v_mfma_f32_16x16x32_bf16 v[100:103], v[162:165], v[198:201], v[100:103]
	v_mfma_f32_16x16x32_bf16 v[96:99], v[170:173], v[198:201], v[96:99]
	s_setprio 2
	s_barrier
	v_mfma_f32_16x16x32_bf16 v[84:87], v[162:165], v[206:209], v[84:87]
	v_mfma_f32_16x16x32_bf16 v[80:83], v[170:173], v[206:209], v[80:83]
	v_mfma_f32_16x16x32_bf16 v[68:71], v[162:165], v[228:231], v[68:71]
	v_mfma_f32_16x16x32_bf16 v[64:67], v[170:173], v[228:231], v[64:67]
	s_setprio 0
	s_add_i32 s64, s64, s46
	v_lshl_add_u64 v[220:221], s[22:23], 0, v[152:153]
	s_mov_b32 m0, s64
	ds_read_b128 v[186:189], v185 offset:16384
	ds_read_b128 v[190:193], v185 offset:17408
	ds_read_b128 v[194:197], v185 offset:18432
	ds_read_b128 v[198:201], v185 offset:19456
	ds_read_b128 v[202:205], v185 offset:20480
	ds_read_b128 v[206:209], v185 offset:21504
	ds_read_b128 v[210:213], v185 offset:22528
	ds_read_b128 v[228:231], v185 offset:23552
	global_load_lds_dwordx4 v[220:221], off
	s_add_i32 m0, s64, 0x2000
	s_add_u32 s64, s22, 0x40000
	v_lshl_add_u64 v[222:223], s[22:23], 0, v[148:149]
	s_addc_u32 s65, s23, 0
	s_add_i32 s68, s68, s46
	global_load_lds_dwordx4 v[222:223], off
	v_lshl_add_u64 v[226:227], s[64:65], 0, v[152:153]
	s_mov_b32 m0, s68
	v_lshl_add_u64 v[232:233], s[24:25], 0, v[150:151]
	global_load_lds_dwordx4 v[226:227], off
	v_lshl_add_u64 v[226:227], s[64:65], 0, v[148:149]
	s_add_i32 m0, s68, 0x2000
	s_nop 0
	global_load_lds_dwordx4 v[226:227], off
	v_lshl_add_u64 v[226:227], s[24:25], 0, v[154:155]
	s_mov_b32 m0, s50
	s_nop 0
	global_load_lds_dwordx4 v[226:227], off
	s_mov_b32 m0, s51
	s_nop 0
	global_load_lds_dwordx4 v[232:233], off
	s_waitcnt vmcnt(8)
	s_waitcnt lgkmcnt(0)
	s_barrier
	s_setprio 1
	v_mfma_f32_16x16x32_bf16 v[60:63], v[128:131], v[186:189], 0
	v_mfma_f32_16x16x32_bf16 v[56:59], v[136:139], v[186:189], 0
	v_mfma_f32_16x16x32_bf16 v[48:51], v[128:131], v[194:197], 0
	v_mfma_f32_16x16x32_bf16 v[40:43], v[136:139], v[194:197], 0
	v_mfma_f32_16x16x32_bf16 v[32:35], v[128:131], v[202:205], 0
	v_mfma_f32_16x16x32_bf16 v[24:27], v[136:139], v[202:205], 0
	v_mfma_f32_16x16x32_bf16 v[16:19], v[128:131], v[210:213], 0
	v_mfma_f32_16x16x32_bf16 v[8:11], v[136:139], v[210:213], 0
	v_mfma_f32_16x16x32_bf16 v[60:63], v[132:135], v[190:193], v[60:63]
	v_mfma_f32_16x16x32_bf16 v[56:59], v[140:143], v[190:193], v[56:59]
	v_mfma_f32_16x16x32_bf16 v[48:51], v[132:135], v[198:201], v[48:51]
	v_mfma_f32_16x16x32_bf16 v[40:43], v[140:143], v[198:201], v[40:43]
	v_mfma_f32_16x16x32_bf16 v[32:35], v[132:135], v[206:209], v[32:35]
	v_mfma_f32_16x16x32_bf16 v[24:27], v[140:143], v[206:209], v[24:27]
	v_mfma_f32_16x16x32_bf16 v[16:19], v[132:135], v[228:231], v[16:19]
	v_mfma_f32_16x16x32_bf16 v[8:11], v[140:143], v[228:231], v[8:11]
	v_mfma_f32_16x16x32_bf16 v[52:55], v[144:147], v[186:189], 0
	v_mfma_f32_16x16x32_bf16 v[44:47], v[166:169], v[186:189], 0
	v_mfma_f32_16x16x32_bf16 v[36:39], v[144:147], v[194:197], 0
	v_mfma_f32_16x16x32_bf16 v[28:31], v[166:169], v[194:197], 0
	v_mfma_f32_16x16x32_bf16 v[20:23], v[144:147], v[202:205], 0
	v_mfma_f32_16x16x32_bf16 v[12:15], v[166:169], v[202:205], 0
	v_mfma_f32_16x16x32_bf16 v[4:7], v[144:147], v[210:213], 0
	v_mfma_f32_16x16x32_bf16 v[0:3], v[166:169], v[210:213], 0
	v_mfma_f32_16x16x32_bf16 v[52:55], v[162:165], v[190:193], v[52:55]
	v_mfma_f32_16x16x32_bf16 v[44:47], v[170:173], v[190:193], v[44:47]
	v_mfma_f32_16x16x32_bf16 v[36:39], v[162:165], v[198:201], v[36:39]
	v_mfma_f32_16x16x32_bf16 v[28:31], v[170:173], v[198:201], v[28:31]
	s_setprio 2
	s_barrier
	v_mfma_f32_16x16x32_bf16 v[20:23], v[162:165], v[206:209], v[20:23]
	v_mfma_f32_16x16x32_bf16 v[12:15], v[170:173], v[206:209], v[12:15]
	v_mfma_f32_16x16x32_bf16 v[4:7], v[162:165], v[228:231], v[4:7]
	v_mfma_f32_16x16x32_bf16 v[0:3], v[170:173], v[228:231], v[0:3]
	s_setprio 0
	s_and_saveexec_b64 s[78:79], s[2:3]
	v_add_f32_e32 v238, v238, v239
	v_add_f32_e32 v240, v240, v241
	v_add_f32_e32 v242, v242, v243
	v_add_f32_e32 v244, v244, v245
	v_add_f32_e32 v246, v246, v247
	v_add_f32_e32 v248, v248, v249
	v_add_f32_e32 v250, v250, v251
	v_add_f32_e32 v252, v252, v253
	v_add_f32_e32 v238, v238, v240
	v_add_f32_e32 v242, v242, v244
	v_add_f32_e32 v246, v246, v248
	v_add_f32_e32 v250, v250, v252
	v_add_f32_e32 v238, v238, v242
	v_add_f32_e32 v246, v246, v250
	v_add_f32_e32 v238, v238, v246
	v_fmamk_f32 v238, v238, 0x3a800000, v216
	v_rsq_f32_e32 v238, v238
	s_nop 0
	ds_write_b32 v183, v238
	s_mov_b64 exec, s[78:79]
	s_add_i32 s64, 0, 0x18000
	s_add_i32 s65, 0, 0x1c000
	v_add_u32_e32 v140, s64, v175
	v_add_u32_e32 v170, s65, v175
	ds_read_b128 v[128:131], v140
	ds_read_b128 v[132:135], v140 offset:1024
	ds_read_b128 v[136:139], v140 offset:2048
	ds_read_b128 v[140:143], v140 offset:3072
	ds_read_b128 v[144:147], v170
	ds_read_b128 v[162:165], v170 offset:1024
	ds_read_b128 v[166:169], v170 offset:2048
	ds_read_b128 v[170:173], v170 offset:3072
	s_add_u32 s24, s24, 0x40000
	s_addc_u32 s25, s25, 0
	s_mov_b32 m0, s52
	v_lshl_add_u64 v[234:235], s[24:25], 0, v[154:155]
	ds_read_b128 v[186:189], v185 offset:32768
	ds_read_b128 v[190:193], v185 offset:33792
	ds_read_b128 v[194:197], v185 offset:34816
	ds_read_b128 v[198:201], v185 offset:35840
	ds_read_b128 v[202:205], v185 offset:36864
	ds_read_b128 v[206:209], v185 offset:37888
	ds_read_b128 v[210:213], v185 offset:38912
	ds_read_b128 v[228:231], v185 offset:39936
	global_load_lds_dwordx4 v[234:235], off
	v_lshl_add_u64 v[234:235], s[24:25], 0, v[150:151]
	s_mov_b32 m0, s53
	s_nop 0
	global_load_lds_dwordx4 v[234:235], off
	s_waitcnt vmcnt(8)
	s_waitcnt lgkmcnt(0)
	s_barrier
	s_setprio 1
	v_mfma_f32_16x16x32_bf16 v[124:127], v[128:131], v[186:189], v[124:127]
	v_mfma_f32_16x16x32_bf16 v[120:123], v[136:139], v[186:189], v[120:123]
	v_mfma_f32_16x16x32_bf16 v[108:111], v[128:131], v[194:197], v[108:111]
	v_mfma_f32_16x16x32_bf16 v[104:107], v[136:139], v[194:197], v[104:107]
	v_mfma_f32_16x16x32_bf16 v[92:95], v[128:131], v[202:205], v[92:95]
	v_mfma_f32_16x16x32_bf16 v[88:91], v[136:139], v[202:205], v[88:91]
	v_mfma_f32_16x16x32_bf16 v[76:79], v[128:131], v[210:213], v[76:79]
	v_mfma_f32_16x16x32_bf16 v[72:75], v[136:139], v[210:213], v[72:75]
	v_mfma_f32_16x16x32_bf16 v[124:127], v[132:135], v[190:193], v[124:127]
	v_mfma_f32_16x16x32_bf16 v[120:123], v[140:143], v[190:193], v[120:123]
	v_mfma_f32_16x16x32_bf16 v[108:111], v[132:135], v[198:201], v[108:111]
	v_mfma_f32_16x16x32_bf16 v[104:107], v[140:143], v[198:201], v[104:107]
	v_mfma_f32_16x16x32_bf16 v[92:95], v[132:135], v[206:209], v[92:95]
	v_mfma_f32_16x16x32_bf16 v[88:91], v[140:143], v[206:209], v[88:91]
	v_mfma_f32_16x16x32_bf16 v[76:79], v[132:135], v[228:231], v[76:79]
	v_mfma_f32_16x16x32_bf16 v[72:75], v[140:143], v[228:231], v[72:75]
	v_mfma_f32_16x16x32_bf16 v[116:119], v[144:147], v[186:189], v[116:119]
	v_mfma_f32_16x16x32_bf16 v[112:115], v[166:169], v[186:189], v[112:115]
	v_mfma_f32_16x16x32_bf16 v[100:103], v[144:147], v[194:197], v[100:103]
	v_mfma_f32_16x16x32_bf16 v[96:99], v[166:169], v[194:197], v[96:99]
	v_mfma_f32_16x16x32_bf16 v[84:87], v[144:147], v[202:205], v[84:87]
	v_mfma_f32_16x16x32_bf16 v[80:83], v[166:169], v[202:205], v[80:83]
	v_mfma_f32_16x16x32_bf16 v[68:71], v[144:147], v[210:213], v[68:71]
	v_mfma_f32_16x16x32_bf16 v[64:67], v[166:169], v[210:213], v[64:67]
	v_mfma_f32_16x16x32_bf16 v[116:119], v[162:165], v[190:193], v[116:119]
	v_mfma_f32_16x16x32_bf16 v[112:115], v[170:173], v[190:193], v[112:115]
	v_mfma_f32_16x16x32_bf16 v[100:103], v[162:165], v[198:201], v[100:103]
	v_mfma_f32_16x16x32_bf16 v[96:99], v[170:173], v[198:201], v[96:99]
	s_setprio 2
	s_barrier
	v_mfma_f32_16x16x32_bf16 v[84:87], v[162:165], v[206:209], v[84:87]
	v_mfma_f32_16x16x32_bf16 v[80:83], v[170:173], v[206:209], v[80:83]
	v_mfma_f32_16x16x32_bf16 v[68:71], v[162:165], v[228:231], v[68:71]
	v_mfma_f32_16x16x32_bf16 v[64:67], v[170:173], v[228:231], v[64:67]
	s_setprio 0
	s_min_i32 s74, s18, 0x80
	s_ashr_i32 s74, s74, 3
	s_mul_hi_i32 s75, s74, 0x3000
	s_mulk_i32 s74, 0x3000
	s_add_u32 s74, s54, s74
	s_addc_u32 s75, s55, s75
	s_lshl_b32 s76, s44, 8
	s_ashr_i32 s77, s76, 31
	s_lshl_b64 s[76:77], s[76:77], 2
	s_add_u32 s74, s74, s76
	s_addc_u32 s75, s75, s77
	v_lshl_add_u64 v[178:179], s[74:75], 0, v[176:177]
	global_load_dwordx4 v[238:241], v[178:179], off
	global_load_dwordx4 v[242:245], v[178:179], off offset:16
	global_load_dwordx4 v[246:249], v[178:179], off offset:512
	global_load_dwordx4 v[250:253], v[178:179], off offset:528
	s_add_i32 s24, s64, s46
	v_lshl_add_u64 v[220:221], v[220:221], 0, s[34:35]
	s_mov_b32 m0, s24
	ds_read_b128 v[186:189], v185 offset:49152
	ds_read_b128 v[190:193], v185 offset:50176
	ds_read_b128 v[194:197], v185 offset:51200
	ds_read_b128 v[198:201], v185 offset:52224
	ds_read_b128 v[202:205], v185 offset:53248
	ds_read_b128 v[206:209], v185 offset:54272
	ds_read_b128 v[210:213], v185 offset:55296
	ds_read_b128 v[228:231], v185 offset:56320
	global_load_lds_dwordx4 v[220:221], off
	s_add_i32 m0, s24, 0x2000
	s_add_u32 s22, s22, 0x40080
	v_lshl_add_u64 v[220:221], v[222:223], 0, s[34:35]
	s_addc_u32 s23, s23, 0
	s_add_i32 s24, s65, s46
	global_load_lds_dwordx4 v[220:221], off
	v_lshl_add_u64 v[220:221], s[22:23], 0, v[152:153]
	s_mov_b32 m0, s24
	s_nop 0
	global_load_lds_dwordx4 v[220:221], off
	v_lshl_add_u64 v[220:221], s[22:23], 0, v[148:149]
	s_add_i32 m0, s24, 0x2000
	s_nop 0
	global_load_lds_dwordx4 v[220:221], off
	v_lshl_add_u64 v[220:221], v[226:227], 0, s[34:35]
	s_mov_b32 m0, s56
	s_nop 0
	global_load_lds_dwordx4 v[220:221], off
	v_lshl_add_u64 v[220:221], v[232:233], 0, s[34:35]
	s_mov_b32 m0, s57
	s_nop 0
	global_load_lds_dwordx4 v[220:221], off
	s_waitcnt vmcnt(12)
	s_waitcnt lgkmcnt(0)
	s_barrier
	s_setprio 1
	v_mfma_f32_16x16x32_bf16 v[60:63], v[128:131], v[186:189], v[60:63]
	v_mfma_f32_16x16x32_bf16 v[56:59], v[136:139], v[186:189], v[56:59]
	v_mfma_f32_16x16x32_bf16 v[48:51], v[128:131], v[194:197], v[48:51]
	v_mfma_f32_16x16x32_bf16 v[40:43], v[136:139], v[194:197], v[40:43]
	v_mfma_f32_16x16x32_bf16 v[32:35], v[128:131], v[202:205], v[32:35]
	v_mfma_f32_16x16x32_bf16 v[24:27], v[136:139], v[202:205], v[24:27]
	v_mfma_f32_16x16x32_bf16 v[16:19], v[128:131], v[210:213], v[16:19]
	v_mfma_f32_16x16x32_bf16 v[8:11], v[136:139], v[210:213], v[8:11]
	v_mfma_f32_16x16x32_bf16 v[60:63], v[132:135], v[190:193], v[60:63]
	v_mfma_f32_16x16x32_bf16 v[56:59], v[140:143], v[190:193], v[56:59]
	v_mfma_f32_16x16x32_bf16 v[48:51], v[132:135], v[198:201], v[48:51]
	v_mfma_f32_16x16x32_bf16 v[40:43], v[140:143], v[198:201], v[40:43]
	v_mfma_f32_16x16x32_bf16 v[32:35], v[132:135], v[206:209], v[32:35]
	v_mfma_f32_16x16x32_bf16 v[24:27], v[140:143], v[206:209], v[24:27]
	v_mfma_f32_16x16x32_bf16 v[16:19], v[132:135], v[228:231], v[16:19]
	v_mfma_f32_16x16x32_bf16 v[8:11], v[140:143], v[228:231], v[8:11]
	v_mfma_f32_16x16x32_bf16 v[52:55], v[144:147], v[186:189], v[52:55]
	v_mfma_f32_16x16x32_bf16 v[44:47], v[166:169], v[186:189], v[44:47]
	v_mfma_f32_16x16x32_bf16 v[36:39], v[144:147], v[194:197], v[36:39]
	v_mfma_f32_16x16x32_bf16 v[28:31], v[166:169], v[194:197], v[28:31]
	v_mfma_f32_16x16x32_bf16 v[20:23], v[144:147], v[202:205], v[20:23]
	v_mfma_f32_16x16x32_bf16 v[12:15], v[166:169], v[202:205], v[12:15]
	v_mfma_f32_16x16x32_bf16 v[4:7], v[144:147], v[210:213], v[4:7]
	v_mfma_f32_16x16x32_bf16 v[0:3], v[166:169], v[210:213], v[0:3]
	v_mfma_f32_16x16x32_bf16 v[52:55], v[162:165], v[190:193], v[52:55]
	v_mfma_f32_16x16x32_bf16 v[44:47], v[170:173], v[190:193], v[44:47]
	v_mfma_f32_16x16x32_bf16 v[36:39], v[162:165], v[198:201], v[36:39]
	v_mfma_f32_16x16x32_bf16 v[28:31], v[170:173], v[198:201], v[28:31]
	s_setprio 2
	s_barrier
	v_mfma_f32_16x16x32_bf16 v[20:23], v[162:165], v[206:209], v[20:23]
	v_mfma_f32_16x16x32_bf16 v[12:15], v[170:173], v[206:209], v[12:15]
	v_mfma_f32_16x16x32_bf16 v[4:7], v[162:165], v[228:231], v[4:7]
	v_mfma_f32_16x16x32_bf16 v[0:3], v[170:173], v[228:231], v[0:3]
	s_setprio 0
	s_add_i32 s63, s63, 2
	s_add_u32 s61, s61, 0x100
	s_addc_u32 s62, s62, 0
	s_add_u32 s20, s20, 0x100
	s_addc_u32 s21, s21, 0
	s_cmp_gt_u32 s63, 13
	s_cbranch_scc1 .Lpeel_exit_1

.LBB0_768:
	s_add_u32 s44, s40, 0x100
	s_addc_u32 s55, s41, 0
	s_mov_b32 s92, -2
	s_add_u32 s40, s8, 0x100
	s_addc_u32 s41, s9, 0
	s_add_i32 s64, 0, 0x10000
	s_cmp_eq_u32 s92, 40
	s_cselect_b32 s53, s1, s41
	s_cselect_b32 s52, s0, s40
	s_cselect_b32 s51, s39, s55
	s_cselect_b32 s50, s38, s44
	s_add_i32 s65, 0, 0x14000
	v_add_u32_e32 v140, s64, v228
	v_add_u32_e32 v156, s65, v228
	ds_read_b128 v[128:131], v140
	ds_read_b128 v[132:135], v140 offset:1024
	ds_read_b128 v[136:139], v140 offset:2048
	ds_read_b128 v[140:143], v140 offset:3072
	ds_read_b128 v[144:147], v156
	ds_read_b128 v[148:151], v156 offset:1024
	ds_read_b128 v[152:155], v156 offset:2048
	ds_read_b128 v[156:159], v156 offset:3072
	v_lshl_add_u64 v[178:179], s[8:9], 0, v[184:185]
	s_add_i32 m0, s62, 0xc000
	ds_read_b128 v[160:163], v231
	ds_read_b128 v[164:167], v231 offset:1024
	ds_read_b128 v[186:189], v231 offset:2048
	ds_read_b128 v[190:193], v231 offset:3072
	ds_read_b128 v[194:197], v231 offset:4096
	ds_read_b128 v[198:201], v231 offset:5120
	ds_read_b128 v[202:205], v231 offset:6144
	ds_read_b128 v[206:209], v231 offset:7168
	global_load_lds_dwordx4 v[178:179], off
	v_lshl_add_u64 v[178:179], s[8:9], 0, v[182:183]
	s_add_i32 m0, s62, 0xe000
	s_nop 0
	global_load_lds_dwordx4 v[178:179], off
	s_waitcnt vmcnt(24)
	s_waitcnt lgkmcnt(0)
	s_barrier
	s_setprio 1
	v_mfma_f32_16x16x32_bf16 v[124:127], v[128:131], v[160:163], 0
	v_mfma_f32_16x16x32_bf16 v[120:123], v[136:139], v[160:163], 0
	v_mfma_f32_16x16x32_bf16 v[108:111], v[128:131], v[186:189], 0
	v_mfma_f32_16x16x32_bf16 v[104:107], v[136:139], v[186:189], 0
	v_mfma_f32_16x16x32_bf16 v[92:95], v[128:131], v[194:197], 0
	v_mfma_f32_16x16x32_bf16 v[88:91], v[136:139], v[194:197], 0
	v_mfma_f32_16x16x32_bf16 v[76:79], v[128:131], v[202:205], 0
	v_mfma_f32_16x16x32_bf16 v[72:75], v[136:139], v[202:205], 0
	v_mfma_f32_16x16x32_bf16 v[124:127], v[132:135], v[164:167], v[124:127]
	v_mfma_f32_16x16x32_bf16 v[120:123], v[140:143], v[164:167], v[120:123]
	v_mfma_f32_16x16x32_bf16 v[108:111], v[132:135], v[190:193], v[108:111]
	v_mfma_f32_16x16x32_bf16 v[104:107], v[140:143], v[190:193], v[104:107]
	v_mfma_f32_16x16x32_bf16 v[92:95], v[132:135], v[198:201], v[92:95]
	v_mfma_f32_16x16x32_bf16 v[88:91], v[140:143], v[198:201], v[88:91]
	v_mfma_f32_16x16x32_bf16 v[76:79], v[132:135], v[206:209], v[76:79]
	v_mfma_f32_16x16x32_bf16 v[72:75], v[140:143], v[206:209], v[72:75]
	v_mfma_f32_16x16x32_bf16 v[116:119], v[144:147], v[160:163], 0
	v_mfma_f32_16x16x32_bf16 v[112:115], v[152:155], v[160:163], 0
	v_mfma_f32_16x16x32_bf16 v[100:103], v[144:147], v[186:189], 0
	v_mfma_f32_16x16x32_bf16 v[96:99], v[152:155], v[186:189], 0
	v_mfma_f32_16x16x32_bf16 v[84:87], v[144:147], v[194:197], 0
	v_mfma_f32_16x16x32_bf16 v[80:83], v[152:155], v[194:197], 0
	v_mfma_f32_16x16x32_bf16 v[68:71], v[144:147], v[202:205], 0
	v_mfma_f32_16x16x32_bf16 v[64:67], v[152:155], v[202:205], 0
	v_mfma_f32_16x16x32_bf16 v[116:119], v[148:151], v[164:167], v[116:119]
	v_mfma_f32_16x16x32_bf16 v[112:115], v[156:159], v[164:167], v[112:115]
	v_mfma_f32_16x16x32_bf16 v[100:103], v[148:151], v[190:193], v[100:103]
	v_mfma_f32_16x16x32_bf16 v[96:99], v[156:159], v[190:193], v[96:99]
	s_setprio 2
	s_barrier
	v_mfma_f32_16x16x32_bf16 v[84:87], v[148:151], v[198:201], v[84:87]
	v_mfma_f32_16x16x32_bf16 v[80:83], v[156:159], v[198:201], v[80:83]
	v_mfma_f32_16x16x32_bf16 v[68:71], v[148:151], v[206:209], v[68:71]
	v_mfma_f32_16x16x32_bf16 v[64:67], v[156:159], v[206:209], v[64:67]
	s_setprio 0
	s_add_i32 s8, s64, s37
	v_lshl_add_u64 v[178:179], s[50:51], 0, v[170:171]
	s_mov_b32 m0, s8
	ds_read_b128 v[160:163], v231 offset:16384
	ds_read_b128 v[164:167], v231 offset:17408
	ds_read_b128 v[186:189], v231 offset:18432
	ds_read_b128 v[190:193], v231 offset:19456
	ds_read_b128 v[194:197], v231 offset:20480
	ds_read_b128 v[198:201], v231 offset:21504
	ds_read_b128 v[202:205], v231 offset:22528
	ds_read_b128 v[206:209], v231 offset:23552
	global_load_lds_dwordx4 v[178:179], off
	s_add_i32 m0, s8, 0x2000
	s_add_u32 s8, s50, 0xb0000
	v_lshl_add_u64 v[210:211], s[50:51], 0, v[174:175]
	s_addc_u32 s9, s51, 0
	s_add_i32 s64, s65, s37
	global_load_lds_dwordx4 v[210:211], off
	v_lshl_add_u64 v[212:213], s[8:9], 0, v[170:171]
	s_mov_b32 m0, s64
	v_lshl_add_u64 v[220:221], s[52:53], 0, v[172:173]
	global_load_lds_dwordx4 v[212:213], off
	v_lshl_add_u64 v[212:213], s[8:9], 0, v[174:175]
	s_add_i32 m0, s64, 0x2000
	s_nop 0
	global_load_lds_dwordx4 v[212:213], off
	v_lshl_add_u64 v[212:213], s[52:53], 0, v[168:169]
	s_mov_b32 m0, s62
	s_nop 0
	global_load_lds_dwordx4 v[212:213], off
	s_mov_b32 m0, s63
	s_nop 0
	global_load_lds_dwordx4 v[220:221], off
	s_waitcnt vmcnt(8)
	s_waitcnt lgkmcnt(0)
	s_barrier
	s_setprio 1
	v_mfma_f32_16x16x32_bf16 v[60:63], v[128:131], v[160:163], 0
	v_mfma_f32_16x16x32_bf16 v[56:59], v[136:139], v[160:163], 0
	v_mfma_f32_16x16x32_bf16 v[44:47], v[128:131], v[186:189], 0
	v_mfma_f32_16x16x32_bf16 v[40:43], v[136:139], v[186:189], 0
	v_mfma_f32_16x16x32_bf16 v[28:31], v[128:131], v[194:197], 0
	v_mfma_f32_16x16x32_bf16 v[24:27], v[136:139], v[194:197], 0
	v_mfma_f32_16x16x32_bf16 v[12:15], v[128:131], v[202:205], 0
	v_mfma_f32_16x16x32_bf16 v[8:11], v[136:139], v[202:205], 0
	v_mfma_f32_16x16x32_bf16 v[60:63], v[132:135], v[164:167], v[60:63]
	v_mfma_f32_16x16x32_bf16 v[56:59], v[140:143], v[164:167], v[56:59]
	v_mfma_f32_16x16x32_bf16 v[44:47], v[132:135], v[190:193], v[44:47]
	v_mfma_f32_16x16x32_bf16 v[40:43], v[140:143], v[190:193], v[40:43]
	v_mfma_f32_16x16x32_bf16 v[28:31], v[132:135], v[198:201], v[28:31]
	v_mfma_f32_16x16x32_bf16 v[24:27], v[140:143], v[198:201], v[24:27]
	v_mfma_f32_16x16x32_bf16 v[12:15], v[132:135], v[206:209], v[12:15]
	v_mfma_f32_16x16x32_bf16 v[8:11], v[140:143], v[206:209], v[8:11]
	v_mfma_f32_16x16x32_bf16 v[52:55], v[144:147], v[160:163], 0
	v_mfma_f32_16x16x32_bf16 v[48:51], v[152:155], v[160:163], 0
	v_mfma_f32_16x16x32_bf16 v[36:39], v[144:147], v[186:189], 0
	v_mfma_f32_16x16x32_bf16 v[32:35], v[152:155], v[186:189], 0
	v_mfma_f32_16x16x32_bf16 v[20:23], v[144:147], v[194:197], 0
	v_mfma_f32_16x16x32_bf16 v[16:19], v[152:155], v[194:197], 0
	v_mfma_f32_16x16x32_bf16 v[4:7], v[144:147], v[202:205], 0
	v_mfma_f32_16x16x32_bf16 v[0:3], v[152:155], v[202:205], 0
	v_mfma_f32_16x16x32_bf16 v[52:55], v[148:151], v[164:167], v[52:55]
	v_mfma_f32_16x16x32_bf16 v[48:51], v[156:159], v[164:167], v[48:51]
	v_mfma_f32_16x16x32_bf16 v[36:39], v[148:151], v[190:193], v[36:39]
	v_mfma_f32_16x16x32_bf16 v[32:35], v[156:159], v[190:193], v[32:35]
	s_setprio 2
	s_barrier
	v_mfma_f32_16x16x32_bf16 v[20:23], v[148:151], v[198:201], v[20:23]
	v_mfma_f32_16x16x32_bf16 v[16:19], v[156:159], v[198:201], v[16:19]
	v_mfma_f32_16x16x32_bf16 v[4:7], v[148:151], v[206:209], v[4:7]
	v_mfma_f32_16x16x32_bf16 v[0:3], v[156:159], v[206:209], v[0:3]
	s_setprio 0
	s_add_i32 s64, 0, 0x18000
	s_add_i32 s65, 0, 0x1c000
	v_add_u32_e32 v140, s64, v228
	v_add_u32_e32 v156, s65, v228
	ds_read_b128 v[128:131], v140
	ds_read_b128 v[132:135], v140 offset:1024
	ds_read_b128 v[136:139], v140 offset:2048
	ds_read_b128 v[140:143], v140 offset:3072
	ds_read_b128 v[144:147], v156
	ds_read_b128 v[148:151], v156 offset:1024
	ds_read_b128 v[152:155], v156 offset:2048
	ds_read_b128 v[156:159], v156 offset:3072
	s_add_u32 s8, s52, 0xb0000
	s_addc_u32 s9, s53, 0
	s_mov_b32 m0, s68
	v_lshl_add_u64 v[222:223], s[8:9], 0, v[168:169]
	ds_read_b128 v[160:163], v231 offset:32768
	ds_read_b128 v[164:167], v231 offset:33792
	ds_read_b128 v[186:189], v231 offset:34816
	ds_read_b128 v[190:193], v231 offset:35840
	ds_read_b128 v[194:197], v231 offset:36864
	ds_read_b128 v[198:201], v231 offset:37888
	ds_read_b128 v[202:205], v231 offset:38912
	ds_read_b128 v[206:209], v231 offset:39936
	global_load_lds_dwordx4 v[222:223], off
	v_lshl_add_u64 v[222:223], s[8:9], 0, v[172:173]
	s_mov_b32 m0, s69
	s_nop 0
	global_load_lds_dwordx4 v[222:223], off
	s_waitcnt vmcnt(8)
	s_waitcnt lgkmcnt(0)
	s_barrier
	s_setprio 1
	v_mfma_f32_16x16x32_bf16 v[124:127], v[128:131], v[160:163], v[124:127]
	v_mfma_f32_16x16x32_bf16 v[120:123], v[136:139], v[160:163], v[120:123]
	v_mfma_f32_16x16x32_bf16 v[108:111], v[128:131], v[186:189], v[108:111]
	v_mfma_f32_16x16x32_bf16 v[104:107], v[136:139], v[186:189], v[104:107]
	v_mfma_f32_16x16x32_bf16 v[92:95], v[128:131], v[194:197], v[92:95]
	v_mfma_f32_16x16x32_bf16 v[88:91], v[136:139], v[194:197], v[88:91]
	v_mfma_f32_16x16x32_bf16 v[76:79], v[128:131], v[202:205], v[76:79]
	v_mfma_f32_16x16x32_bf16 v[72:75], v[136:139], v[202:205], v[72:75]
	v_mfma_f32_16x16x32_bf16 v[124:127], v[132:135], v[164:167], v[124:127]
	v_mfma_f32_16x16x32_bf16 v[120:123], v[140:143], v[164:167], v[120:123]
	v_mfma_f32_16x16x32_bf16 v[108:111], v[132:135], v[190:193], v[108:111]
	v_mfma_f32_16x16x32_bf16 v[104:107], v[140:143], v[190:193], v[104:107]
	v_mfma_f32_16x16x32_bf16 v[92:95], v[132:135], v[198:201], v[92:95]
	v_mfma_f32_16x16x32_bf16 v[88:91], v[140:143], v[198:201], v[88:91]
	v_mfma_f32_16x16x32_bf16 v[76:79], v[132:135], v[206:209], v[76:79]
	v_mfma_f32_16x16x32_bf16 v[72:75], v[140:143], v[206:209], v[72:75]
	v_mfma_f32_16x16x32_bf16 v[116:119], v[144:147], v[160:163], v[116:119]
	v_mfma_f32_16x16x32_bf16 v[112:115], v[152:155], v[160:163], v[112:115]
	v_mfma_f32_16x16x32_bf16 v[100:103], v[144:147], v[186:189], v[100:103]
	v_mfma_f32_16x16x32_bf16 v[96:99], v[152:155], v[186:189], v[96:99]
	v_mfma_f32_16x16x32_bf16 v[84:87], v[144:147], v[194:197], v[84:87]
	v_mfma_f32_16x16x32_bf16 v[80:83], v[152:155], v[194:197], v[80:83]
	v_mfma_f32_16x16x32_bf16 v[68:71], v[144:147], v[202:205], v[68:71]
	v_mfma_f32_16x16x32_bf16 v[64:67], v[152:155], v[202:205], v[64:67]
	v_mfma_f32_16x16x32_bf16 v[116:119], v[148:151], v[164:167], v[116:119]
	v_mfma_f32_16x16x32_bf16 v[112:115], v[156:159], v[164:167], v[112:115]
	v_mfma_f32_16x16x32_bf16 v[100:103], v[148:151], v[190:193], v[100:103]
	v_mfma_f32_16x16x32_bf16 v[96:99], v[156:159], v[190:193], v[96:99]
	s_setprio 2
	s_barrier
	v_mfma_f32_16x16x32_bf16 v[84:87], v[148:151], v[198:201], v[84:87]
	v_mfma_f32_16x16x32_bf16 v[80:83], v[156:159], v[198:201], v[80:83]
	v_mfma_f32_16x16x32_bf16 v[68:71], v[148:151], v[206:209], v[68:71]
	v_mfma_f32_16x16x32_bf16 v[64:67], v[156:159], v[206:209], v[64:67]
	s_setprio 0
	s_add_i32 s8, s64, s37
	v_lshl_add_u64 v[178:179], v[178:179], 0, s[34:35]
	s_mov_b32 m0, s8
	ds_read_b128 v[160:163], v231 offset:49152
	ds_read_b128 v[164:167], v231 offset:50176
	ds_read_b128 v[186:189], v231 offset:51200
	ds_read_b128 v[190:193], v231 offset:52224
	ds_read_b128 v[194:197], v231 offset:53248
	ds_read_b128 v[198:201], v231 offset:54272
	ds_read_b128 v[202:205], v231 offset:55296
	ds_read_b128 v[206:209], v231 offset:56320
	global_load_lds_dwordx4 v[178:179], off
	s_add_i32 m0, s8, 0x2000
	s_add_u32 s8, s50, 0xb0080
	v_lshl_add_u64 v[178:179], v[210:211], 0, s[34:35]
	s_addc_u32 s9, s51, 0
	s_add_i32 s50, s65, s37
	global_load_lds_dwordx4 v[178:179], off
	v_lshl_add_u64 v[178:179], s[8:9], 0, v[170:171]
	s_mov_b32 m0, s50
	s_nop 0
	global_load_lds_dwordx4 v[178:179], off
	v_lshl_add_u64 v[178:179], s[8:9], 0, v[174:175]
	s_add_i32 m0, s50, 0x2000
	s_nop 0
	global_load_lds_dwordx4 v[178:179], off
	v_lshl_add_u64 v[178:179], v[212:213], 0, s[34:35]
	s_mov_b32 m0, s73
	s_nop 0
	global_load_lds_dwordx4 v[178:179], off
	v_lshl_add_u64 v[178:179], v[220:221], 0, s[34:35]
	s_mov_b32 m0, s74
	s_nop 0
	global_load_lds_dwordx4 v[178:179], off
	s_waitcnt vmcnt(8)
	s_waitcnt lgkmcnt(0)
	s_barrier
	s_setprio 1
	v_mfma_f32_16x16x32_bf16 v[60:63], v[128:131], v[160:163], v[60:63]
	v_mfma_f32_16x16x32_bf16 v[56:59], v[136:139], v[160:163], v[56:59]
	v_mfma_f32_16x16x32_bf16 v[44:47], v[128:131], v[186:189], v[44:47]
	v_mfma_f32_16x16x32_bf16 v[40:43], v[136:139], v[186:189], v[40:43]
	v_mfma_f32_16x16x32_bf16 v[28:31], v[128:131], v[194:197], v[28:31]
	v_mfma_f32_16x16x32_bf16 v[24:27], v[136:139], v[194:197], v[24:27]
	v_mfma_f32_16x16x32_bf16 v[12:15], v[128:131], v[202:205], v[12:15]
	v_mfma_f32_16x16x32_bf16 v[8:11], v[136:139], v[202:205], v[8:11]
	v_mfma_f32_16x16x32_bf16 v[60:63], v[132:135], v[164:167], v[60:63]
	v_mfma_f32_16x16x32_bf16 v[56:59], v[140:143], v[164:167], v[56:59]
	v_mfma_f32_16x16x32_bf16 v[44:47], v[132:135], v[190:193], v[44:47]
	v_mfma_f32_16x16x32_bf16 v[40:43], v[140:143], v[190:193], v[40:43]
	v_mfma_f32_16x16x32_bf16 v[28:31], v[132:135], v[198:201], v[28:31]
	v_mfma_f32_16x16x32_bf16 v[24:27], v[140:143], v[198:201], v[24:27]
	v_mfma_f32_16x16x32_bf16 v[12:15], v[132:135], v[206:209], v[12:15]
	v_mfma_f32_16x16x32_bf16 v[8:11], v[140:143], v[206:209], v[8:11]
	v_mfma_f32_16x16x32_bf16 v[52:55], v[144:147], v[160:163], v[52:55]
	v_mfma_f32_16x16x32_bf16 v[48:51], v[152:155], v[160:163], v[48:51]
	v_mfma_f32_16x16x32_bf16 v[36:39], v[144:147], v[186:189], v[36:39]
	v_mfma_f32_16x16x32_bf16 v[32:35], v[152:155], v[186:189], v[32:35]
	v_mfma_f32_16x16x32_bf16 v[20:23], v[144:147], v[194:197], v[20:23]
	v_mfma_f32_16x16x32_bf16 v[16:19], v[152:155], v[194:197], v[16:19]
	v_mfma_f32_16x16x32_bf16 v[4:7], v[144:147], v[202:205], v[4:7]
	v_mfma_f32_16x16x32_bf16 v[0:3], v[152:155], v[202:205], v[0:3]
	v_mfma_f32_16x16x32_bf16 v[52:55], v[148:151], v[164:167], v[52:55]
	v_mfma_f32_16x16x32_bf16 v[48:51], v[156:159], v[164:167], v[48:51]
	v_mfma_f32_16x16x32_bf16 v[36:39], v[148:151], v[190:193], v[36:39]
	v_mfma_f32_16x16x32_bf16 v[32:35], v[156:159], v[190:193], v[32:35]
	s_setprio 2
	s_barrier
	v_mfma_f32_16x16x32_bf16 v[20:23], v[148:151], v[198:201], v[20:23]
	v_mfma_f32_16x16x32_bf16 v[16:19], v[156:159], v[198:201], v[16:19]
	v_mfma_f32_16x16x32_bf16 v[4:7], v[148:151], v[206:209], v[4:7]
	v_mfma_f32_16x16x32_bf16 v[0:3], v[156:159], v[206:209], v[0:3]
	s_setprio 0
	s_add_i32 s92, s92, 2
	s_add_u32 s44, s44, 0x100
	s_addc_u32 s55, s55, 0
	s_cmp_gt_u32 s92, 41
	s_mov_b64 s[8:9], s[40:41]
	s_cbranch_scc1 .Lpeel_exit_2

.LBB0_862:
	s_add_i32 s27, s63, -2
	s_add_u32 vcc_lo, s40, 0x100
	s_addc_u32 vcc_hi, s41, 0
	s_mov_b32 s50, 0
	s_add_i32 s64, s50, 2
	s_add_u32 s40, s8, 0x100
	s_addc_u32 s41, s9, 0
	s_add_i32 s65, 0, 0x10000
	s_cmp_eq_u32 s27, s50
	s_cselect_b32 s53, s29, s41
	s_cselect_b32 s52, s28, s40
	s_cselect_b32 s51, s39, vcc_hi
	s_cselect_b32 s50, s38, vcc_lo
	s_add_i32 s66, 0, 0x14000
	v_add_u32_e32 v140, s65, v228
	v_add_u32_e32 v156, s66, v228
	ds_read_b128 v[128:131], v140
	ds_read_b128 v[132:135], v140 offset:1024
	ds_read_b128 v[136:139], v140 offset:2048
	ds_read_b128 v[140:143], v140 offset:3072
	ds_read_b128 v[144:147], v156
	ds_read_b128 v[148:151], v156 offset:1024
	ds_read_b128 v[152:155], v156 offset:2048
	ds_read_b128 v[156:159], v156 offset:3072
	v_lshl_add_u64 v[178:179], s[8:9], 0, v[184:185]
	s_add_i32 m0, s74, 0xc000
	ds_read_b128 v[160:163], v232
	ds_read_b128 v[164:167], v232 offset:1024
	ds_read_b128 v[186:189], v232 offset:2048
	ds_read_b128 v[190:193], v232 offset:3072
	ds_read_b128 v[194:197], v232 offset:4096
	ds_read_b128 v[198:201], v232 offset:5120
	ds_read_b128 v[202:205], v232 offset:6144
	ds_read_b128 v[206:209], v232 offset:7168
	global_load_lds_dwordx4 v[178:179], off
	v_lshl_add_u64 v[178:179], s[8:9], 0, v[182:183]
	s_add_i32 m0, s74, 0xe000
	s_nop 0
	global_load_lds_dwordx4 v[178:179], off
	s_waitcnt vmcnt(24)
	s_waitcnt lgkmcnt(0)
	s_barrier
	s_setprio 1
	v_mfma_f32_16x16x32_bf16 v[124:127], v[128:131], v[160:163], 0
	v_mfma_f32_16x16x32_bf16 v[120:123], v[136:139], v[160:163], 0
	v_mfma_f32_16x16x32_bf16 v[108:111], v[128:131], v[186:189], 0
	v_mfma_f32_16x16x32_bf16 v[104:107], v[136:139], v[186:189], 0
	v_mfma_f32_16x16x32_bf16 v[92:95], v[128:131], v[194:197], 0
	v_mfma_f32_16x16x32_bf16 v[88:91], v[136:139], v[194:197], 0
	v_mfma_f32_16x16x32_bf16 v[76:79], v[128:131], v[202:205], 0
	v_mfma_f32_16x16x32_bf16 v[72:75], v[136:139], v[202:205], 0
	v_mfma_f32_16x16x32_bf16 v[124:127], v[132:135], v[164:167], v[124:127]
	v_mfma_f32_16x16x32_bf16 v[120:123], v[140:143], v[164:167], v[120:123]
	v_mfma_f32_16x16x32_bf16 v[108:111], v[132:135], v[190:193], v[108:111]
	v_mfma_f32_16x16x32_bf16 v[104:107], v[140:143], v[190:193], v[104:107]
	v_mfma_f32_16x16x32_bf16 v[92:95], v[132:135], v[198:201], v[92:95]
	v_mfma_f32_16x16x32_bf16 v[88:91], v[140:143], v[198:201], v[88:91]
	v_mfma_f32_16x16x32_bf16 v[76:79], v[132:135], v[206:209], v[76:79]
	v_mfma_f32_16x16x32_bf16 v[72:75], v[140:143], v[206:209], v[72:75]
	v_mfma_f32_16x16x32_bf16 v[116:119], v[144:147], v[160:163], 0
	v_mfma_f32_16x16x32_bf16 v[112:115], v[152:155], v[160:163], 0
	v_mfma_f32_16x16x32_bf16 v[100:103], v[144:147], v[186:189], 0
	v_mfma_f32_16x16x32_bf16 v[96:99], v[152:155], v[186:189], 0
	v_mfma_f32_16x16x32_bf16 v[84:87], v[144:147], v[194:197], 0
	v_mfma_f32_16x16x32_bf16 v[80:83], v[152:155], v[194:197], 0
	v_mfma_f32_16x16x32_bf16 v[68:71], v[144:147], v[202:205], 0
	v_mfma_f32_16x16x32_bf16 v[64:67], v[152:155], v[202:205], 0
	v_mfma_f32_16x16x32_bf16 v[116:119], v[148:151], v[164:167], v[116:119]
	v_mfma_f32_16x16x32_bf16 v[112:115], v[156:159], v[164:167], v[112:115]
	v_mfma_f32_16x16x32_bf16 v[100:103], v[148:151], v[190:193], v[100:103]
	v_mfma_f32_16x16x32_bf16 v[96:99], v[156:159], v[190:193], v[96:99]
	s_setprio 2
	s_barrier
	v_mfma_f32_16x16x32_bf16 v[84:87], v[148:151], v[198:201], v[84:87]
	v_mfma_f32_16x16x32_bf16 v[80:83], v[156:159], v[198:201], v[80:83]
	v_mfma_f32_16x16x32_bf16 v[68:71], v[148:151], v[206:209], v[68:71]
	v_mfma_f32_16x16x32_bf16 v[64:67], v[156:159], v[206:209], v[64:67]
	s_setprio 0
	s_add_i32 s8, s65, s72
	v_lshl_add_u64 v[178:179], s[50:51], 0, v[170:171]
	s_mov_b32 m0, s8
	ds_read_b128 v[160:163], v232 offset:16384
	ds_read_b128 v[164:167], v232 offset:17408
	ds_read_b128 v[186:189], v232 offset:18432
	ds_read_b128 v[190:193], v232 offset:19456
	ds_read_b128 v[194:197], v232 offset:20480
	ds_read_b128 v[198:201], v232 offset:21504
	ds_read_b128 v[202:205], v232 offset:22528
	ds_read_b128 v[206:209], v232 offset:23552
	global_load_lds_dwordx4 v[178:179], off
	s_add_i32 m0, s8, 0x2000
	s_add_u32 s8, s50, 0xb0000
	v_lshl_add_u64 v[210:211], s[50:51], 0, v[174:175]
	s_addc_u32 s9, s51, 0
	s_add_i32 s65, s66, s72
	global_load_lds_dwordx4 v[210:211], off
	v_lshl_add_u64 v[212:213], s[8:9], 0, v[170:171]
	s_mov_b32 m0, s65
	v_lshl_add_u64 v[220:221], s[52:53], 0, v[172:173]
	global_load_lds_dwordx4 v[212:213], off
	v_lshl_add_u64 v[212:213], s[8:9], 0, v[174:175]
	s_add_i32 m0, s65, 0x2000
	s_nop 0
	global_load_lds_dwordx4 v[212:213], off
	v_lshl_add_u64 v[212:213], s[52:53], 0, v[168:169]
	s_mov_b32 m0, s74
	s_nop 0
	global_load_lds_dwordx4 v[212:213], off
	s_mov_b32 m0, s75
	s_nop 0
	global_load_lds_dwordx4 v[220:221], off
	s_waitcnt vmcnt(8)
	s_waitcnt lgkmcnt(0)
	s_barrier
	s_setprio 1
	v_mfma_f32_16x16x32_bf16 v[60:63], v[128:131], v[160:163], 0
	v_mfma_f32_16x16x32_bf16 v[56:59], v[136:139], v[160:163], 0
	v_mfma_f32_16x16x32_bf16 v[44:47], v[128:131], v[186:189], 0
	v_mfma_f32_16x16x32_bf16 v[40:43], v[136:139], v[186:189], 0
	v_mfma_f32_16x16x32_bf16 v[28:31], v[128:131], v[194:197], 0
	v_mfma_f32_16x16x32_bf16 v[24:27], v[136:139], v[194:197], 0
	v_mfma_f32_16x16x32_bf16 v[12:15], v[128:131], v[202:205], 0
	v_mfma_f32_16x16x32_bf16 v[8:11], v[136:139], v[202:205], 0
	v_mfma_f32_16x16x32_bf16 v[60:63], v[132:135], v[164:167], v[60:63]
	v_mfma_f32_16x16x32_bf16 v[56:59], v[140:143], v[164:167], v[56:59]
	v_mfma_f32_16x16x32_bf16 v[44:47], v[132:135], v[190:193], v[44:47]
	v_mfma_f32_16x16x32_bf16 v[40:43], v[140:143], v[190:193], v[40:43]
	v_mfma_f32_16x16x32_bf16 v[28:31], v[132:135], v[198:201], v[28:31]
	v_mfma_f32_16x16x32_bf16 v[24:27], v[140:143], v[198:201], v[24:27]
	v_mfma_f32_16x16x32_bf16 v[12:15], v[132:135], v[206:209], v[12:15]
	v_mfma_f32_16x16x32_bf16 v[8:11], v[140:143], v[206:209], v[8:11]
	v_mfma_f32_16x16x32_bf16 v[52:55], v[144:147], v[160:163], 0
	v_mfma_f32_16x16x32_bf16 v[48:51], v[152:155], v[160:163], 0
	v_mfma_f32_16x16x32_bf16 v[36:39], v[144:147], v[186:189], 0
	v_mfma_f32_16x16x32_bf16 v[32:35], v[152:155], v[186:189], 0
	v_mfma_f32_16x16x32_bf16 v[20:23], v[144:147], v[194:197], 0
	v_mfma_f32_16x16x32_bf16 v[16:19], v[152:155], v[194:197], 0
	v_mfma_f32_16x16x32_bf16 v[4:7], v[144:147], v[202:205], 0
	v_mfma_f32_16x16x32_bf16 v[0:3], v[152:155], v[202:205], 0
	v_mfma_f32_16x16x32_bf16 v[52:55], v[148:151], v[164:167], v[52:55]
	v_mfma_f32_16x16x32_bf16 v[48:51], v[156:159], v[164:167], v[48:51]
	v_mfma_f32_16x16x32_bf16 v[36:39], v[148:151], v[190:193], v[36:39]
	v_mfma_f32_16x16x32_bf16 v[32:35], v[156:159], v[190:193], v[32:35]
	s_setprio 2
	s_barrier
	v_mfma_f32_16x16x32_bf16 v[20:23], v[148:151], v[198:201], v[20:23]
	v_mfma_f32_16x16x32_bf16 v[16:19], v[156:159], v[198:201], v[16:19]
	v_mfma_f32_16x16x32_bf16 v[4:7], v[148:151], v[206:209], v[4:7]
	v_mfma_f32_16x16x32_bf16 v[0:3], v[156:159], v[206:209], v[0:3]
	s_setprio 0
	s_add_i32 s65, 0, 0x18000
	s_add_i32 s66, 0, 0x1c000
	v_add_u32_e32 v140, s65, v228
	v_add_u32_e32 v156, s66, v228
	ds_read_b128 v[128:131], v140
	ds_read_b128 v[132:135], v140 offset:1024
	ds_read_b128 v[136:139], v140 offset:2048
	ds_read_b128 v[140:143], v140 offset:3072
	ds_read_b128 v[144:147], v156
	ds_read_b128 v[148:151], v156 offset:1024
	ds_read_b128 v[152:155], v156 offset:2048
	ds_read_b128 v[156:159], v156 offset:3072
	s_add_u32 s8, s52, 0xb0000
	s_addc_u32 s9, s53, 0
	s_mov_b32 m0, s80
	v_lshl_add_u64 v[222:223], s[8:9], 0, v[168:169]
	ds_read_b128 v[160:163], v232 offset:32768
	ds_read_b128 v[164:167], v232 offset:33792
	ds_read_b128 v[186:189], v232 offset:34816
	ds_read_b128 v[190:193], v232 offset:35840
	ds_read_b128 v[194:197], v232 offset:36864
	ds_read_b128 v[198:201], v232 offset:37888
	ds_read_b128 v[202:205], v232 offset:38912
	ds_read_b128 v[206:209], v232 offset:39936
	global_load_lds_dwordx4 v[222:223], off
	v_lshl_add_u64 v[222:223], s[8:9], 0, v[172:173]
	s_mov_b32 m0, s81
	s_nop 0
	global_load_lds_dwordx4 v[222:223], off
	s_waitcnt vmcnt(8)
	s_waitcnt lgkmcnt(0)
	s_barrier
	s_setprio 1
	v_mfma_f32_16x16x32_bf16 v[124:127], v[128:131], v[160:163], v[124:127]
	v_mfma_f32_16x16x32_bf16 v[120:123], v[136:139], v[160:163], v[120:123]
	v_mfma_f32_16x16x32_bf16 v[108:111], v[128:131], v[186:189], v[108:111]
	v_mfma_f32_16x16x32_bf16 v[104:107], v[136:139], v[186:189], v[104:107]
	v_mfma_f32_16x16x32_bf16 v[92:95], v[128:131], v[194:197], v[92:95]
	v_mfma_f32_16x16x32_bf16 v[88:91], v[136:139], v[194:197], v[88:91]
	v_mfma_f32_16x16x32_bf16 v[76:79], v[128:131], v[202:205], v[76:79]
	v_mfma_f32_16x16x32_bf16 v[72:75], v[136:139], v[202:205], v[72:75]
	v_mfma_f32_16x16x32_bf16 v[124:127], v[132:135], v[164:167], v[124:127]
	v_mfma_f32_16x16x32_bf16 v[120:123], v[140:143], v[164:167], v[120:123]
	v_mfma_f32_16x16x32_bf16 v[108:111], v[132:135], v[190:193], v[108:111]
	v_mfma_f32_16x16x32_bf16 v[104:107], v[140:143], v[190:193], v[104:107]
	v_mfma_f32_16x16x32_bf16 v[92:95], v[132:135], v[198:201], v[92:95]
	v_mfma_f32_16x16x32_bf16 v[88:91], v[140:143], v[198:201], v[88:91]
	v_mfma_f32_16x16x32_bf16 v[76:79], v[132:135], v[206:209], v[76:79]
	v_mfma_f32_16x16x32_bf16 v[72:75], v[140:143], v[206:209], v[72:75]
	v_mfma_f32_16x16x32_bf16 v[116:119], v[144:147], v[160:163], v[116:119]
	v_mfma_f32_16x16x32_bf16 v[112:115], v[152:155], v[160:163], v[112:115]
	v_mfma_f32_16x16x32_bf16 v[100:103], v[144:147], v[186:189], v[100:103]
	v_mfma_f32_16x16x32_bf16 v[96:99], v[152:155], v[186:189], v[96:99]
	v_mfma_f32_16x16x32_bf16 v[84:87], v[144:147], v[194:197], v[84:87]
	v_mfma_f32_16x16x32_bf16 v[80:83], v[152:155], v[194:197], v[80:83]
	v_mfma_f32_16x16x32_bf16 v[68:71], v[144:147], v[202:205], v[68:71]
	v_mfma_f32_16x16x32_bf16 v[64:67], v[152:155], v[202:205], v[64:67]
	v_mfma_f32_16x16x32_bf16 v[116:119], v[148:151], v[164:167], v[116:119]
	v_mfma_f32_16x16x32_bf16 v[112:115], v[156:159], v[164:167], v[112:115]
	v_mfma_f32_16x16x32_bf16 v[100:103], v[148:151], v[190:193], v[100:103]
	v_mfma_f32_16x16x32_bf16 v[96:99], v[156:159], v[190:193], v[96:99]
	s_setprio 2
	s_barrier
	v_mfma_f32_16x16x32_bf16 v[84:87], v[148:151], v[198:201], v[84:87]
	v_mfma_f32_16x16x32_bf16 v[80:83], v[156:159], v[198:201], v[80:83]
	v_mfma_f32_16x16x32_bf16 v[68:71], v[148:151], v[206:209], v[68:71]
	v_mfma_f32_16x16x32_bf16 v[64:67], v[156:159], v[206:209], v[64:67]
	s_setprio 0
	s_add_i32 s8, s65, s72
	v_lshl_add_u64 v[178:179], v[178:179], 0, s[34:35]
	s_mov_b32 m0, s8
	ds_read_b128 v[160:163], v232 offset:49152
	ds_read_b128 v[164:167], v232 offset:50176
	ds_read_b128 v[186:189], v232 offset:51200
	ds_read_b128 v[190:193], v232 offset:52224
	ds_read_b128 v[194:197], v232 offset:53248
	ds_read_b128 v[198:201], v232 offset:54272
	ds_read_b128 v[202:205], v232 offset:55296
	ds_read_b128 v[206:209], v232 offset:56320
	global_load_lds_dwordx4 v[178:179], off
	s_add_i32 m0, s8, 0x2000
	s_add_u32 s8, s50, 0xb0080
	v_lshl_add_u64 v[178:179], v[210:211], 0, s[34:35]
	s_addc_u32 s9, s51, 0
	s_add_i32 s50, s66, s72
	global_load_lds_dwordx4 v[178:179], off
	v_lshl_add_u64 v[178:179], s[8:9], 0, v[170:171]
	s_mov_b32 m0, s50
	s_nop 0
	global_load_lds_dwordx4 v[178:179], off
	v_lshl_add_u64 v[178:179], s[8:9], 0, v[174:175]
	s_add_i32 m0, s50, 0x2000
	s_nop 0
	global_load_lds_dwordx4 v[178:179], off
	v_lshl_add_u64 v[178:179], v[212:213], 0, s[34:35]
	s_mov_b32 m0, s83
	s_nop 0
	global_load_lds_dwordx4 v[178:179], off
	v_lshl_add_u64 v[178:179], v[220:221], 0, s[34:35]
	s_mov_b32 m0, s91
	s_nop 0
	global_load_lds_dwordx4 v[178:179], off
	s_waitcnt vmcnt(8)
	s_waitcnt lgkmcnt(0)
	s_barrier
	s_setprio 1
	v_mfma_f32_16x16x32_bf16 v[60:63], v[128:131], v[160:163], v[60:63]
	v_mfma_f32_16x16x32_bf16 v[56:59], v[136:139], v[160:163], v[56:59]
	v_mfma_f32_16x16x32_bf16 v[44:47], v[128:131], v[186:189], v[44:47]
	v_mfma_f32_16x16x32_bf16 v[40:43], v[136:139], v[186:189], v[40:43]
	v_mfma_f32_16x16x32_bf16 v[28:31], v[128:131], v[194:197], v[28:31]
	v_mfma_f32_16x16x32_bf16 v[24:27], v[136:139], v[194:197], v[24:27]
	v_mfma_f32_16x16x32_bf16 v[12:15], v[128:131], v[202:205], v[12:15]
	v_mfma_f32_16x16x32_bf16 v[8:11], v[136:139], v[202:205], v[8:11]
	v_mfma_f32_16x16x32_bf16 v[60:63], v[132:135], v[164:167], v[60:63]
	v_mfma_f32_16x16x32_bf16 v[56:59], v[140:143], v[164:167], v[56:59]
	v_mfma_f32_16x16x32_bf16 v[44:47], v[132:135], v[190:193], v[44:47]
	v_mfma_f32_16x16x32_bf16 v[40:43], v[140:143], v[190:193], v[40:43]
	v_mfma_f32_16x16x32_bf16 v[28:31], v[132:135], v[198:201], v[28:31]
	v_mfma_f32_16x16x32_bf16 v[24:27], v[140:143], v[198:201], v[24:27]
	v_mfma_f32_16x16x32_bf16 v[12:15], v[132:135], v[206:209], v[12:15]
	v_mfma_f32_16x16x32_bf16 v[8:11], v[140:143], v[206:209], v[8:11]
	v_mfma_f32_16x16x32_bf16 v[52:55], v[144:147], v[160:163], v[52:55]
	v_mfma_f32_16x16x32_bf16 v[48:51], v[152:155], v[160:163], v[48:51]
	v_mfma_f32_16x16x32_bf16 v[36:39], v[144:147], v[186:189], v[36:39]
	v_mfma_f32_16x16x32_bf16 v[32:35], v[152:155], v[186:189], v[32:35]
	v_mfma_f32_16x16x32_bf16 v[20:23], v[144:147], v[194:197], v[20:23]
	v_mfma_f32_16x16x32_bf16 v[16:19], v[152:155], v[194:197], v[16:19]
	v_mfma_f32_16x16x32_bf16 v[4:7], v[144:147], v[202:205], v[4:7]
	v_mfma_f32_16x16x32_bf16 v[0:3], v[152:155], v[202:205], v[0:3]
	v_mfma_f32_16x16x32_bf16 v[52:55], v[148:151], v[164:167], v[52:55]
	v_mfma_f32_16x16x32_bf16 v[48:51], v[156:159], v[164:167], v[48:51]
	v_mfma_f32_16x16x32_bf16 v[36:39], v[148:151], v[190:193], v[36:39]
	v_mfma_f32_16x16x32_bf16 v[32:35], v[156:159], v[190:193], v[32:35]
	s_setprio 2
	s_barrier
	v_mfma_f32_16x16x32_bf16 v[20:23], v[148:151], v[198:201], v[20:23]
	v_mfma_f32_16x16x32_bf16 v[16:19], v[156:159], v[198:201], v[16:19]
	v_mfma_f32_16x16x32_bf16 v[4:7], v[148:151], v[206:209], v[4:7]
	v_mfma_f32_16x16x32_bf16 v[0:3], v[156:159], v[206:209], v[0:3]
	s_setprio 0
	s_add_u32 vcc_lo, vcc_lo, 0x100
	s_addc_u32 vcc_hi, vcc_hi, 0
	s_cmp_ge_i32 s64, s63
	s_mov_b64 s[8:9], s[40:41]
	s_mov_b32 s50, s64
	s_cbranch_scc1 .Lpeel_exit_3

.LBB0_952:
	s_add_u32 s44, s38, 0x180
	s_addc_u32 s53, s39, 0
	s_mov_b32 s83, -2
	s_add_u32 s38, s8, 0x180
	s_addc_u32 s39, s9, 0
	s_add_i32 s64, 0, 0x10000
	s_cmp_eq_u32 s83, 12
	s_cselect_b32 s51, s1, s39
	s_cselect_b32 s50, s0, s38
	s_cselect_b32 s41, s29, s53
	s_cselect_b32 s40, s28, s44
	s_add_i32 s65, 0, 0x14000
	v_add_u32_e32 v68, s64, v228
	v_add_u32_e32 v156, s65, v228
	ds_read_b128 v[56:59], v68
	ds_read_b128 v[60:63], v68 offset:1024
	ds_read_b128 v[64:67], v68 offset:2048
	ds_read_b128 v[68:71], v68 offset:3072
	ds_read_b128 v[144:147], v156
	ds_read_b128 v[148:151], v156 offset:1024
	ds_read_b128 v[152:155], v156 offset:2048
	ds_read_b128 v[156:159], v156 offset:3072
	v_lshl_add_u64 v[178:179], s[8:9], 0, v[192:193]
	s_add_i32 m0, s60, 0xc000
	ds_read_b128 v[160:163], v231
	ds_read_b128 v[164:167], v231 offset:1024
	ds_read_b128 v[168:171], v231 offset:2048
	ds_read_b128 v[172:175], v231 offset:3072
	ds_read_b128 v[194:197], v231 offset:4096
	ds_read_b128 v[198:201], v231 offset:5120
	ds_read_b128 v[202:205], v231 offset:6144
	ds_read_b128 v[206:209], v231 offset:7168
	global_load_lds_dwordx4 v[178:179], off
	v_lshl_add_u64 v[178:179], s[8:9], 0, v[190:191]
	s_add_i32 m0, s60, 0xe000
	s_nop 0
	global_load_lds_dwordx4 v[178:179], off
	s_waitcnt vmcnt(24)
	s_waitcnt lgkmcnt(0)
	s_barrier
	s_setprio 1
	v_mfma_f32_16x16x32_bf16 v[140:143], v[56:59], v[160:163], 0
	v_mfma_f32_16x16x32_bf16 v[136:139], v[64:67], v[160:163], 0
	v_mfma_f32_16x16x32_bf16 v[128:131], v[56:59], v[168:171], 0
	v_mfma_f32_16x16x32_bf16 v[120:123], v[64:67], v[168:171], 0
	v_mfma_f32_16x16x32_bf16 v[108:111], v[56:59], v[194:197], 0
	v_mfma_f32_16x16x32_bf16 v[104:107], v[64:67], v[194:197], 0
	v_mfma_f32_16x16x32_bf16 v[92:95], v[56:59], v[202:205], 0
	v_mfma_f32_16x16x32_bf16 v[88:91], v[64:67], v[202:205], 0
	v_mfma_f32_16x16x32_bf16 v[140:143], v[60:63], v[164:167], v[140:143]
	v_mfma_f32_16x16x32_bf16 v[136:139], v[68:71], v[164:167], v[136:139]
	v_mfma_f32_16x16x32_bf16 v[128:131], v[60:63], v[172:175], v[128:131]
	v_mfma_f32_16x16x32_bf16 v[120:123], v[68:71], v[172:175], v[120:123]
	v_mfma_f32_16x16x32_bf16 v[108:111], v[60:63], v[198:201], v[108:111]
	v_mfma_f32_16x16x32_bf16 v[104:107], v[68:71], v[198:201], v[104:107]
	v_mfma_f32_16x16x32_bf16 v[92:95], v[60:63], v[206:209], v[92:95]
	v_mfma_f32_16x16x32_bf16 v[88:91], v[68:71], v[206:209], v[88:91]
	v_mfma_f32_16x16x32_bf16 v[132:135], v[144:147], v[160:163], 0
	v_mfma_f32_16x16x32_bf16 v[124:127], v[152:155], v[160:163], 0
	v_mfma_f32_16x16x32_bf16 v[116:119], v[144:147], v[168:171], 0
	v_mfma_f32_16x16x32_bf16 v[112:115], v[152:155], v[168:171], 0
	v_mfma_f32_16x16x32_bf16 v[100:103], v[144:147], v[194:197], 0
	v_mfma_f32_16x16x32_bf16 v[96:99], v[152:155], v[194:197], 0
	v_mfma_f32_16x16x32_bf16 v[84:87], v[144:147], v[202:205], 0
	v_mfma_f32_16x16x32_bf16 v[80:83], v[152:155], v[202:205], 0
	v_mfma_f32_16x16x32_bf16 v[132:135], v[148:151], v[164:167], v[132:135]
	v_mfma_f32_16x16x32_bf16 v[124:127], v[156:159], v[164:167], v[124:127]
	v_mfma_f32_16x16x32_bf16 v[116:119], v[148:151], v[172:175], v[116:119]
	v_mfma_f32_16x16x32_bf16 v[112:115], v[156:159], v[172:175], v[112:115]
	s_setprio 2
	s_barrier
	v_mfma_f32_16x16x32_bf16 v[100:103], v[148:151], v[198:201], v[100:103]
	v_mfma_f32_16x16x32_bf16 v[96:99], v[156:159], v[198:201], v[96:99]
	v_mfma_f32_16x16x32_bf16 v[84:87], v[148:151], v[206:209], v[84:87]
	v_mfma_f32_16x16x32_bf16 v[80:83], v[156:159], v[206:209], v[80:83]
	s_setprio 0
	s_add_i32 s8, s64, s37
	v_lshl_add_u64 v[178:179], s[40:41], 0, v[184:185]
	s_mov_b32 m0, s8
	ds_read_b128 v[160:163], v231 offset:16384
	ds_read_b128 v[164:167], v231 offset:17408
	ds_read_b128 v[168:171], v231 offset:18432
	ds_read_b128 v[172:175], v231 offset:19456
	ds_read_b128 v[194:197], v231 offset:20480
	ds_read_b128 v[198:201], v231 offset:21504
	ds_read_b128 v[202:205], v231 offset:22528
	ds_read_b128 v[206:209], v231 offset:23552
	global_load_lds_dwordx4 v[178:179], off
	s_add_i32 m0, s8, 0x2000
	s_add_u32 s8, s40, 0x60000
	v_lshl_add_u64 v[210:211], s[40:41], 0, v[188:189]
	s_addc_u32 s9, s41, 0
	s_add_i32 s64, s65, s37
	global_load_lds_dwordx4 v[210:211], off
	v_lshl_add_u64 v[212:213], s[8:9], 0, v[184:185]
	s_mov_b32 m0, s64
	v_lshl_add_u64 v[220:221], s[50:51], 0, v[186:187]
	global_load_lds_dwordx4 v[212:213], off
	v_lshl_add_u64 v[212:213], s[8:9], 0, v[188:189]
	s_add_i32 m0, s64, 0x2000
	s_nop 0
	global_load_lds_dwordx4 v[212:213], off
	v_lshl_add_u64 v[212:213], s[50:51], 0, v[182:183]
	s_mov_b32 m0, s60
	s_nop 0
	global_load_lds_dwordx4 v[212:213], off
	s_mov_b32 m0, s61
	s_nop 0
	global_load_lds_dwordx4 v[220:221], off
	s_waitcnt vmcnt(8)
	s_waitcnt lgkmcnt(0)
	s_barrier
	s_setprio 1
	v_mfma_f32_16x16x32_bf16 v[76:79], v[56:59], v[160:163], 0
	v_mfma_f32_16x16x32_bf16 v[72:75], v[64:67], v[160:163], 0
	v_mfma_f32_16x16x32_bf16 v[44:47], v[56:59], v[168:171], 0
	v_mfma_f32_16x16x32_bf16 v[40:43], v[64:67], v[168:171], 0
	v_mfma_f32_16x16x32_bf16 v[28:31], v[56:59], v[194:197], 0
	v_mfma_f32_16x16x32_bf16 v[24:27], v[64:67], v[194:197], 0
	v_mfma_f32_16x16x32_bf16 v[12:15], v[56:59], v[202:205], 0
	v_mfma_f32_16x16x32_bf16 v[8:11], v[64:67], v[202:205], 0
	v_mfma_f32_16x16x32_bf16 v[76:79], v[60:63], v[164:167], v[76:79]
	v_mfma_f32_16x16x32_bf16 v[72:75], v[68:71], v[164:167], v[72:75]
	v_mfma_f32_16x16x32_bf16 v[44:47], v[60:63], v[172:175], v[44:47]
	v_mfma_f32_16x16x32_bf16 v[40:43], v[68:71], v[172:175], v[40:43]
	v_mfma_f32_16x16x32_bf16 v[28:31], v[60:63], v[198:201], v[28:31]
	v_mfma_f32_16x16x32_bf16 v[24:27], v[68:71], v[198:201], v[24:27]
	v_mfma_f32_16x16x32_bf16 v[12:15], v[60:63], v[206:209], v[12:15]
	v_mfma_f32_16x16x32_bf16 v[8:11], v[68:71], v[206:209], v[8:11]
	v_mfma_f32_16x16x32_bf16 v[52:55], v[144:147], v[160:163], 0
	v_mfma_f32_16x16x32_bf16 v[48:51], v[152:155], v[160:163], 0
	v_mfma_f32_16x16x32_bf16 v[36:39], v[144:147], v[168:171], 0
	v_mfma_f32_16x16x32_bf16 v[32:35], v[152:155], v[168:171], 0
	v_mfma_f32_16x16x32_bf16 v[20:23], v[144:147], v[194:197], 0
	v_mfma_f32_16x16x32_bf16 v[16:19], v[152:155], v[194:197], 0
	v_mfma_f32_16x16x32_bf16 v[4:7], v[144:147], v[202:205], 0
	v_mfma_f32_16x16x32_bf16 v[0:3], v[152:155], v[202:205], 0
	v_mfma_f32_16x16x32_bf16 v[52:55], v[148:151], v[164:167], v[52:55]
	v_mfma_f32_16x16x32_bf16 v[48:51], v[156:159], v[164:167], v[48:51]
	v_mfma_f32_16x16x32_bf16 v[36:39], v[148:151], v[172:175], v[36:39]
	v_mfma_f32_16x16x32_bf16 v[32:35], v[156:159], v[172:175], v[32:35]
	s_setprio 2
	s_barrier
	v_mfma_f32_16x16x32_bf16 v[20:23], v[148:151], v[198:201], v[20:23]
	v_mfma_f32_16x16x32_bf16 v[16:19], v[156:159], v[198:201], v[16:19]
	v_mfma_f32_16x16x32_bf16 v[4:7], v[148:151], v[206:209], v[4:7]
	v_mfma_f32_16x16x32_bf16 v[0:3], v[156:159], v[206:209], v[0:3]
	s_setprio 0
	s_add_i32 s64, 0, 0x18000
	s_add_i32 s65, 0, 0x1c000
	v_add_u32_e32 v68, s64, v228
	v_add_u32_e32 v156, s65, v228
	ds_read_b128 v[56:59], v68
	ds_read_b128 v[60:63], v68 offset:1024
	ds_read_b128 v[64:67], v68 offset:2048
	ds_read_b128 v[68:71], v68 offset:3072
	ds_read_b128 v[144:147], v156
	ds_read_b128 v[148:151], v156 offset:1024
	ds_read_b128 v[152:155], v156 offset:2048
	ds_read_b128 v[156:159], v156 offset:3072
	s_add_u32 s8, s50, 0x60000
	s_addc_u32 s9, s51, 0
	s_mov_b32 m0, s62
	v_lshl_add_u64 v[222:223], s[8:9], 0, v[182:183]
	ds_read_b128 v[160:163], v231 offset:32768
	ds_read_b128 v[164:167], v231 offset:33792
	ds_read_b128 v[168:171], v231 offset:34816
	ds_read_b128 v[172:175], v231 offset:35840
	ds_read_b128 v[194:197], v231 offset:36864
	ds_read_b128 v[198:201], v231 offset:37888
	ds_read_b128 v[202:205], v231 offset:38912
	ds_read_b128 v[206:209], v231 offset:39936
	global_load_lds_dwordx4 v[222:223], off
	v_lshl_add_u64 v[222:223], s[8:9], 0, v[186:187]
	s_mov_b32 m0, s63
	s_nop 0
	global_load_lds_dwordx4 v[222:223], off
	s_waitcnt vmcnt(8)
	s_waitcnt lgkmcnt(0)
	s_barrier
	s_setprio 1
	v_mfma_f32_16x16x32_bf16 v[140:143], v[56:59], v[160:163], v[140:143]
	v_mfma_f32_16x16x32_bf16 v[136:139], v[64:67], v[160:163], v[136:139]
	v_mfma_f32_16x16x32_bf16 v[128:131], v[56:59], v[168:171], v[128:131]
	v_mfma_f32_16x16x32_bf16 v[120:123], v[64:67], v[168:171], v[120:123]
	v_mfma_f32_16x16x32_bf16 v[108:111], v[56:59], v[194:197], v[108:111]
	v_mfma_f32_16x16x32_bf16 v[104:107], v[64:67], v[194:197], v[104:107]
	v_mfma_f32_16x16x32_bf16 v[92:95], v[56:59], v[202:205], v[92:95]
	v_mfma_f32_16x16x32_bf16 v[88:91], v[64:67], v[202:205], v[88:91]
	v_mfma_f32_16x16x32_bf16 v[140:143], v[60:63], v[164:167], v[140:143]
	v_mfma_f32_16x16x32_bf16 v[136:139], v[68:71], v[164:167], v[136:139]
	v_mfma_f32_16x16x32_bf16 v[128:131], v[60:63], v[172:175], v[128:131]
	v_mfma_f32_16x16x32_bf16 v[120:123], v[68:71], v[172:175], v[120:123]
	v_mfma_f32_16x16x32_bf16 v[108:111], v[60:63], v[198:201], v[108:111]
	v_mfma_f32_16x16x32_bf16 v[104:107], v[68:71], v[198:201], v[104:107]
	v_mfma_f32_16x16x32_bf16 v[92:95], v[60:63], v[206:209], v[92:95]
	v_mfma_f32_16x16x32_bf16 v[88:91], v[68:71], v[206:209], v[88:91]
	v_mfma_f32_16x16x32_bf16 v[132:135], v[144:147], v[160:163], v[132:135]
	v_mfma_f32_16x16x32_bf16 v[124:127], v[152:155], v[160:163], v[124:127]
	v_mfma_f32_16x16x32_bf16 v[116:119], v[144:147], v[168:171], v[116:119]
	v_mfma_f32_16x16x32_bf16 v[112:115], v[152:155], v[168:171], v[112:115]
	v_mfma_f32_16x16x32_bf16 v[100:103], v[144:147], v[194:197], v[100:103]
	v_mfma_f32_16x16x32_bf16 v[96:99], v[152:155], v[194:197], v[96:99]
	v_mfma_f32_16x16x32_bf16 v[84:87], v[144:147], v[202:205], v[84:87]
	v_mfma_f32_16x16x32_bf16 v[80:83], v[152:155], v[202:205], v[80:83]
	v_mfma_f32_16x16x32_bf16 v[132:135], v[148:151], v[164:167], v[132:135]
	v_mfma_f32_16x16x32_bf16 v[124:127], v[156:159], v[164:167], v[124:127]
	v_mfma_f32_16x16x32_bf16 v[116:119], v[148:151], v[172:175], v[116:119]
	v_mfma_f32_16x16x32_bf16 v[112:115], v[156:159], v[172:175], v[112:115]
	s_setprio 2
	s_barrier
	v_mfma_f32_16x16x32_bf16 v[100:103], v[148:151], v[198:201], v[100:103]
	v_mfma_f32_16x16x32_bf16 v[96:99], v[156:159], v[198:201], v[96:99]
	v_mfma_f32_16x16x32_bf16 v[84:87], v[148:151], v[206:209], v[84:87]
	v_mfma_f32_16x16x32_bf16 v[80:83], v[156:159], v[206:209], v[80:83]
	s_setprio 0
	s_add_i32 s8, s64, s37
	v_lshl_add_u64 v[178:179], v[178:179], 0, s[34:35]
	s_mov_b32 m0, s8
	ds_read_b128 v[160:163], v231 offset:49152
	ds_read_b128 v[164:167], v231 offset:50176
	ds_read_b128 v[168:171], v231 offset:51200
	ds_read_b128 v[172:175], v231 offset:52224
	ds_read_b128 v[194:197], v231 offset:53248
	ds_read_b128 v[198:201], v231 offset:54272
	ds_read_b128 v[202:205], v231 offset:55296
	ds_read_b128 v[206:209], v231 offset:56320
	global_load_lds_dwordx4 v[178:179], off
	s_add_i32 m0, s8, 0x2000
	s_add_u32 s8, s40, 0x60080
	v_lshl_add_u64 v[178:179], v[210:211], 0, s[34:35]
	s_addc_u32 s9, s41, 0
	s_add_i32 s40, s65, s37
	global_load_lds_dwordx4 v[178:179], off
	v_lshl_add_u64 v[178:179], s[8:9], 0, v[184:185]
	s_mov_b32 m0, s40
	s_nop 0
	global_load_lds_dwordx4 v[178:179], off
	v_lshl_add_u64 v[178:179], s[8:9], 0, v[188:189]
	s_add_i32 m0, s40, 0x2000
	s_nop 0
	global_load_lds_dwordx4 v[178:179], off
	v_lshl_add_u64 v[178:179], v[212:213], 0, s[34:35]
	s_mov_b32 m0, s69
	s_nop 0
	global_load_lds_dwordx4 v[178:179], off
	v_lshl_add_u64 v[178:179], v[220:221], 0, s[34:35]
	s_mov_b32 m0, s72
	s_nop 0
	global_load_lds_dwordx4 v[178:179], off
	s_waitcnt vmcnt(8)
	s_waitcnt lgkmcnt(0)
	s_barrier
	s_setprio 1
	v_mfma_f32_16x16x32_bf16 v[76:79], v[56:59], v[160:163], v[76:79]
	v_mfma_f32_16x16x32_bf16 v[72:75], v[64:67], v[160:163], v[72:75]
	v_mfma_f32_16x16x32_bf16 v[44:47], v[56:59], v[168:171], v[44:47]
	v_mfma_f32_16x16x32_bf16 v[40:43], v[64:67], v[168:171], v[40:43]
	v_mfma_f32_16x16x32_bf16 v[28:31], v[56:59], v[194:197], v[28:31]
	v_mfma_f32_16x16x32_bf16 v[24:27], v[64:67], v[194:197], v[24:27]
	v_mfma_f32_16x16x32_bf16 v[12:15], v[56:59], v[202:205], v[12:15]
	v_mfma_f32_16x16x32_bf16 v[8:11], v[64:67], v[202:205], v[8:11]
	v_mfma_f32_16x16x32_bf16 v[76:79], v[60:63], v[164:167], v[76:79]
	v_mfma_f32_16x16x32_bf16 v[72:75], v[68:71], v[164:167], v[72:75]
	v_mfma_f32_16x16x32_bf16 v[44:47], v[60:63], v[172:175], v[44:47]
	v_mfma_f32_16x16x32_bf16 v[40:43], v[68:71], v[172:175], v[40:43]
	v_mfma_f32_16x16x32_bf16 v[28:31], v[60:63], v[198:201], v[28:31]
	v_mfma_f32_16x16x32_bf16 v[24:27], v[68:71], v[198:201], v[24:27]
	v_mfma_f32_16x16x32_bf16 v[12:15], v[60:63], v[206:209], v[12:15]
	v_mfma_f32_16x16x32_bf16 v[8:11], v[68:71], v[206:209], v[8:11]
	v_mfma_f32_16x16x32_bf16 v[52:55], v[144:147], v[160:163], v[52:55]
	v_mfma_f32_16x16x32_bf16 v[48:51], v[152:155], v[160:163], v[48:51]
	v_mfma_f32_16x16x32_bf16 v[36:39], v[144:147], v[168:171], v[36:39]
	v_mfma_f32_16x16x32_bf16 v[32:35], v[152:155], v[168:171], v[32:35]
	v_mfma_f32_16x16x32_bf16 v[20:23], v[144:147], v[194:197], v[20:23]
	v_mfma_f32_16x16x32_bf16 v[16:19], v[152:155], v[194:197], v[16:19]
	v_mfma_f32_16x16x32_bf16 v[4:7], v[144:147], v[202:205], v[4:7]
	v_mfma_f32_16x16x32_bf16 v[0:3], v[152:155], v[202:205], v[0:3]
	v_mfma_f32_16x16x32_bf16 v[52:55], v[148:151], v[164:167], v[52:55]
	v_mfma_f32_16x16x32_bf16 v[48:51], v[156:159], v[164:167], v[48:51]
	v_mfma_f32_16x16x32_bf16 v[36:39], v[148:151], v[172:175], v[36:39]
	v_mfma_f32_16x16x32_bf16 v[32:35], v[156:159], v[172:175], v[32:35]
	s_setprio 2
	s_barrier
	v_mfma_f32_16x16x32_bf16 v[20:23], v[148:151], v[198:201], v[20:23]
	v_mfma_f32_16x16x32_bf16 v[16:19], v[156:159], v[198:201], v[16:19]
	v_mfma_f32_16x16x32_bf16 v[4:7], v[148:151], v[206:209], v[4:7]
	v_mfma_f32_16x16x32_bf16 v[0:3], v[156:159], v[206:209], v[0:3]
	s_setprio 0
	s_add_i32 s83, s83, 2
	s_add_u32 s44, s44, 0x180
	s_addc_u32 s53, s53, 0
	s_cmp_gt_u32 s83, 13
	s_mov_b64 s[8:9], s[38:39]
	s_cbranch_scc1 .Lpeel_exit_4

.LBB0_1045:
	s_add_i32 s25, s63, -2
	s_add_u32 s93, s38, 0x180
	s_addc_u32 s94, s39, 0
	s_mov_b32 s40, 0
	s_add_i32 s64, s40, 2
	s_add_u32 s38, s8, 0x180
	s_addc_u32 s39, s9, 0
	s_add_i32 s65, 0, 0x10000
	s_cmp_eq_u32 s25, s40
	s_cselect_b32 s51, s27, s39
	s_cselect_b32 s50, s26, s38
	s_cselect_b32 s41, s29, s94
	s_cselect_b32 s40, s28, s93
	s_add_i32 s66, 0, 0x14000
	v_add_u32_e32 v108, s65, v228
	v_add_u32_e32 v156, s66, v228
	ds_read_b128 v[88:91], v108
	ds_read_b128 v[92:95], v108 offset:1024
	ds_read_b128 v[104:107], v108 offset:2048
	ds_read_b128 v[108:111], v108 offset:3072
	ds_read_b128 v[144:147], v156
	ds_read_b128 v[148:151], v156 offset:1024
	ds_read_b128 v[152:155], v156 offset:2048
	ds_read_b128 v[156:159], v156 offset:3072
	v_lshl_add_u64 v[178:179], s[8:9], 0, v[192:193]
	s_add_i32 m0, s72, 0xc000
	ds_read_b128 v[160:163], v232
	ds_read_b128 v[164:167], v232 offset:1024
	ds_read_b128 v[168:171], v232 offset:2048
	ds_read_b128 v[172:175], v232 offset:3072
	ds_read_b128 v[194:197], v232 offset:4096
	ds_read_b128 v[198:201], v232 offset:5120
	ds_read_b128 v[202:205], v232 offset:6144
	ds_read_b128 v[206:209], v232 offset:7168
	global_load_lds_dwordx4 v[178:179], off
	v_lshl_add_u64 v[178:179], s[8:9], 0, v[190:191]
	s_add_i32 m0, s72, 0xe000
	s_nop 0
	global_load_lds_dwordx4 v[178:179], off
	s_waitcnt vmcnt(24)
	s_waitcnt lgkmcnt(0)
	s_barrier
	s_setprio 1
	v_mfma_f32_16x16x32_bf16 v[140:143], v[88:91], v[160:163], 0
	v_mfma_f32_16x16x32_bf16 v[136:139], v[104:107], v[160:163], 0
	v_mfma_f32_16x16x32_bf16 v[124:127], v[88:91], v[168:171], 0
	v_mfma_f32_16x16x32_bf16 v[120:123], v[104:107], v[168:171], 0
	v_mfma_f32_16x16x32_bf16 v[100:103], v[88:91], v[194:197], 0
	v_mfma_f32_16x16x32_bf16 v[96:99], v[104:107], v[194:197], 0
	v_mfma_f32_16x16x32_bf16 v[76:79], v[88:91], v[202:205], 0
	v_mfma_f32_16x16x32_bf16 v[72:75], v[104:107], v[202:205], 0
	v_mfma_f32_16x16x32_bf16 v[140:143], v[92:95], v[164:167], v[140:143]
	v_mfma_f32_16x16x32_bf16 v[136:139], v[108:111], v[164:167], v[136:139]
	v_mfma_f32_16x16x32_bf16 v[124:127], v[92:95], v[172:175], v[124:127]
	v_mfma_f32_16x16x32_bf16 v[120:123], v[108:111], v[172:175], v[120:123]
	v_mfma_f32_16x16x32_bf16 v[100:103], v[92:95], v[198:201], v[100:103]
	v_mfma_f32_16x16x32_bf16 v[96:99], v[108:111], v[198:201], v[96:99]
	v_mfma_f32_16x16x32_bf16 v[76:79], v[92:95], v[206:209], v[76:79]
	v_mfma_f32_16x16x32_bf16 v[72:75], v[108:111], v[206:209], v[72:75]
	v_mfma_f32_16x16x32_bf16 v[132:135], v[144:147], v[160:163], 0
	v_mfma_f32_16x16x32_bf16 v[128:131], v[152:155], v[160:163], 0
	v_mfma_f32_16x16x32_bf16 v[116:119], v[144:147], v[168:171], 0
	v_mfma_f32_16x16x32_bf16 v[112:115], v[152:155], v[168:171], 0
	v_mfma_f32_16x16x32_bf16 v[84:87], v[144:147], v[194:197], 0
	v_mfma_f32_16x16x32_bf16 v[80:83], v[152:155], v[194:197], 0
	v_mfma_f32_16x16x32_bf16 v[68:71], v[144:147], v[202:205], 0
	v_mfma_f32_16x16x32_bf16 v[64:67], v[152:155], v[202:205], 0
	v_mfma_f32_16x16x32_bf16 v[132:135], v[148:151], v[164:167], v[132:135]
	v_mfma_f32_16x16x32_bf16 v[128:131], v[156:159], v[164:167], v[128:131]
	v_mfma_f32_16x16x32_bf16 v[116:119], v[148:151], v[172:175], v[116:119]
	v_mfma_f32_16x16x32_bf16 v[112:115], v[156:159], v[172:175], v[112:115]
	s_setprio 2
	s_barrier
	v_mfma_f32_16x16x32_bf16 v[84:87], v[148:151], v[198:201], v[84:87]
	v_mfma_f32_16x16x32_bf16 v[80:83], v[156:159], v[198:201], v[80:83]
	v_mfma_f32_16x16x32_bf16 v[68:71], v[148:151], v[206:209], v[68:71]
	v_mfma_f32_16x16x32_bf16 v[64:67], v[156:159], v[206:209], v[64:67]
	s_setprio 0
	s_add_i32 s8, s65, s68
	v_lshl_add_u64 v[178:179], s[40:41], 0, v[184:185]
	s_mov_b32 m0, s8
	ds_read_b128 v[160:163], v232 offset:16384
	ds_read_b128 v[164:167], v232 offset:17408
	ds_read_b128 v[168:171], v232 offset:18432
	ds_read_b128 v[172:175], v232 offset:19456
	ds_read_b128 v[194:197], v232 offset:20480
	ds_read_b128 v[198:201], v232 offset:21504
	ds_read_b128 v[202:205], v232 offset:22528
	ds_read_b128 v[206:209], v232 offset:23552
	global_load_lds_dwordx4 v[178:179], off
	s_add_i32 m0, s8, 0x2000
	s_add_u32 s8, s40, 0x60000
	v_lshl_add_u64 v[210:211], s[40:41], 0, v[188:189]
	s_addc_u32 s9, s41, 0
	s_add_i32 s65, s66, s68
	global_load_lds_dwordx4 v[210:211], off
	v_lshl_add_u64 v[212:213], s[8:9], 0, v[184:185]
	s_mov_b32 m0, s65
	v_lshl_add_u64 v[220:221], s[50:51], 0, v[186:187]
	global_load_lds_dwordx4 v[212:213], off
	v_lshl_add_u64 v[212:213], s[8:9], 0, v[188:189]
	s_add_i32 m0, s65, 0x2000
	s_nop 0
	global_load_lds_dwordx4 v[212:213], off
	v_lshl_add_u64 v[212:213], s[50:51], 0, v[182:183]
	s_mov_b32 m0, s72
	s_nop 0
	global_load_lds_dwordx4 v[212:213], off
	s_mov_b32 m0, s73
	s_nop 0
	global_load_lds_dwordx4 v[220:221], off
	s_waitcnt vmcnt(8)
	s_waitcnt lgkmcnt(0)
	s_barrier
	s_setprio 1
	v_mfma_f32_16x16x32_bf16 v[60:63], v[88:91], v[160:163], 0
	v_mfma_f32_16x16x32_bf16 v[56:59], v[104:107], v[160:163], 0
	v_mfma_f32_16x16x32_bf16 v[44:47], v[88:91], v[168:171], 0
	v_mfma_f32_16x16x32_bf16 v[40:43], v[104:107], v[168:171], 0
	v_mfma_f32_16x16x32_bf16 v[28:31], v[88:91], v[194:197], 0
	v_mfma_f32_16x16x32_bf16 v[24:27], v[104:107], v[194:197], 0
	v_mfma_f32_16x16x32_bf16 v[12:15], v[88:91], v[202:205], 0
	v_mfma_f32_16x16x32_bf16 v[8:11], v[104:107], v[202:205], 0
	v_mfma_f32_16x16x32_bf16 v[60:63], v[92:95], v[164:167], v[60:63]
	v_mfma_f32_16x16x32_bf16 v[56:59], v[108:111], v[164:167], v[56:59]
	v_mfma_f32_16x16x32_bf16 v[44:47], v[92:95], v[172:175], v[44:47]
	v_mfma_f32_16x16x32_bf16 v[40:43], v[108:111], v[172:175], v[40:43]
	v_mfma_f32_16x16x32_bf16 v[28:31], v[92:95], v[198:201], v[28:31]
	v_mfma_f32_16x16x32_bf16 v[24:27], v[108:111], v[198:201], v[24:27]
	v_mfma_f32_16x16x32_bf16 v[12:15], v[92:95], v[206:209], v[12:15]
	v_mfma_f32_16x16x32_bf16 v[8:11], v[108:111], v[206:209], v[8:11]
	v_mfma_f32_16x16x32_bf16 v[52:55], v[144:147], v[160:163], 0
	v_mfma_f32_16x16x32_bf16 v[48:51], v[152:155], v[160:163], 0
	v_mfma_f32_16x16x32_bf16 v[36:39], v[144:147], v[168:171], 0
	v_mfma_f32_16x16x32_bf16 v[32:35], v[152:155], v[168:171], 0
	v_mfma_f32_16x16x32_bf16 v[20:23], v[144:147], v[194:197], 0
	v_mfma_f32_16x16x32_bf16 v[16:19], v[152:155], v[194:197], 0
	v_mfma_f32_16x16x32_bf16 v[4:7], v[144:147], v[202:205], 0
	v_mfma_f32_16x16x32_bf16 v[0:3], v[152:155], v[202:205], 0
	v_mfma_f32_16x16x32_bf16 v[52:55], v[148:151], v[164:167], v[52:55]
	v_mfma_f32_16x16x32_bf16 v[48:51], v[156:159], v[164:167], v[48:51]
	v_mfma_f32_16x16x32_bf16 v[36:39], v[148:151], v[172:175], v[36:39]
	v_mfma_f32_16x16x32_bf16 v[32:35], v[156:159], v[172:175], v[32:35]
	s_setprio 2
	s_barrier
	v_mfma_f32_16x16x32_bf16 v[20:23], v[148:151], v[198:201], v[20:23]
	v_mfma_f32_16x16x32_bf16 v[16:19], v[156:159], v[198:201], v[16:19]
	v_mfma_f32_16x16x32_bf16 v[4:7], v[148:151], v[206:209], v[4:7]
	v_mfma_f32_16x16x32_bf16 v[0:3], v[156:159], v[206:209], v[0:3]
	s_setprio 0
	s_add_i32 s65, 0, 0x18000
	s_add_i32 s66, 0, 0x1c000
	v_add_u32_e32 v108, s65, v228
	v_add_u32_e32 v156, s66, v228
	ds_read_b128 v[88:91], v108
	ds_read_b128 v[92:95], v108 offset:1024
	ds_read_b128 v[104:107], v108 offset:2048
	ds_read_b128 v[108:111], v108 offset:3072
	ds_read_b128 v[144:147], v156
	ds_read_b128 v[148:151], v156 offset:1024
	ds_read_b128 v[152:155], v156 offset:2048
	ds_read_b128 v[156:159], v156 offset:3072
	s_add_u32 s8, s50, 0x60000
	s_addc_u32 s9, s51, 0
	s_mov_b32 m0, s74
	v_lshl_add_u64 v[222:223], s[8:9], 0, v[182:183]
	ds_read_b128 v[160:163], v232 offset:32768
	ds_read_b128 v[164:167], v232 offset:33792
	ds_read_b128 v[168:171], v232 offset:34816
	ds_read_b128 v[172:175], v232 offset:35840
	ds_read_b128 v[194:197], v232 offset:36864
	ds_read_b128 v[198:201], v232 offset:37888
	ds_read_b128 v[202:205], v232 offset:38912
	ds_read_b128 v[206:209], v232 offset:39936
	global_load_lds_dwordx4 v[222:223], off
	v_lshl_add_u64 v[222:223], s[8:9], 0, v[186:187]
	s_mov_b32 m0, s75
	s_nop 0
	global_load_lds_dwordx4 v[222:223], off
	s_waitcnt vmcnt(8)
	s_waitcnt lgkmcnt(0)
	s_barrier
	s_setprio 1
	v_mfma_f32_16x16x32_bf16 v[140:143], v[88:91], v[160:163], v[140:143]
	v_mfma_f32_16x16x32_bf16 v[136:139], v[104:107], v[160:163], v[136:139]
	v_mfma_f32_16x16x32_bf16 v[124:127], v[88:91], v[168:171], v[124:127]
	v_mfma_f32_16x16x32_bf16 v[120:123], v[104:107], v[168:171], v[120:123]
	v_mfma_f32_16x16x32_bf16 v[100:103], v[88:91], v[194:197], v[100:103]
	v_mfma_f32_16x16x32_bf16 v[96:99], v[104:107], v[194:197], v[96:99]
	v_mfma_f32_16x16x32_bf16 v[76:79], v[88:91], v[202:205], v[76:79]
	v_mfma_f32_16x16x32_bf16 v[72:75], v[104:107], v[202:205], v[72:75]
	v_mfma_f32_16x16x32_bf16 v[140:143], v[92:95], v[164:167], v[140:143]
	v_mfma_f32_16x16x32_bf16 v[136:139], v[108:111], v[164:167], v[136:139]
	v_mfma_f32_16x16x32_bf16 v[124:127], v[92:95], v[172:175], v[124:127]
	v_mfma_f32_16x16x32_bf16 v[120:123], v[108:111], v[172:175], v[120:123]
	v_mfma_f32_16x16x32_bf16 v[100:103], v[92:95], v[198:201], v[100:103]
	v_mfma_f32_16x16x32_bf16 v[96:99], v[108:111], v[198:201], v[96:99]
	v_mfma_f32_16x16x32_bf16 v[76:79], v[92:95], v[206:209], v[76:79]
	v_mfma_f32_16x16x32_bf16 v[72:75], v[108:111], v[206:209], v[72:75]
	v_mfma_f32_16x16x32_bf16 v[132:135], v[144:147], v[160:163], v[132:135]
	v_mfma_f32_16x16x32_bf16 v[128:131], v[152:155], v[160:163], v[128:131]
	v_mfma_f32_16x16x32_bf16 v[116:119], v[144:147], v[168:171], v[116:119]
	v_mfma_f32_16x16x32_bf16 v[112:115], v[152:155], v[168:171], v[112:115]
	v_mfma_f32_16x16x32_bf16 v[84:87], v[144:147], v[194:197], v[84:87]
	v_mfma_f32_16x16x32_bf16 v[80:83], v[152:155], v[194:197], v[80:83]
	v_mfma_f32_16x16x32_bf16 v[68:71], v[144:147], v[202:205], v[68:71]
	v_mfma_f32_16x16x32_bf16 v[64:67], v[152:155], v[202:205], v[64:67]
	v_mfma_f32_16x16x32_bf16 v[132:135], v[148:151], v[164:167], v[132:135]
	v_mfma_f32_16x16x32_bf16 v[128:131], v[156:159], v[164:167], v[128:131]
	v_mfma_f32_16x16x32_bf16 v[116:119], v[148:151], v[172:175], v[116:119]
	v_mfma_f32_16x16x32_bf16 v[112:115], v[156:159], v[172:175], v[112:115]
	s_setprio 2
	s_barrier
	v_mfma_f32_16x16x32_bf16 v[84:87], v[148:151], v[198:201], v[84:87]
	v_mfma_f32_16x16x32_bf16 v[80:83], v[156:159], v[198:201], v[80:83]
	v_mfma_f32_16x16x32_bf16 v[68:71], v[148:151], v[206:209], v[68:71]
	v_mfma_f32_16x16x32_bf16 v[64:67], v[156:159], v[206:209], v[64:67]
	s_setprio 0
	s_add_i32 s8, s65, s68
	v_lshl_add_u64 v[178:179], v[178:179], 0, s[34:35]
	s_mov_b32 m0, s8
	ds_read_b128 v[160:163], v232 offset:49152
	ds_read_b128 v[164:167], v232 offset:50176
	ds_read_b128 v[168:171], v232 offset:51200
	ds_read_b128 v[172:175], v232 offset:52224
	ds_read_b128 v[194:197], v232 offset:53248
	ds_read_b128 v[198:201], v232 offset:54272
	ds_read_b128 v[202:205], v232 offset:55296
	ds_read_b128 v[206:209], v232 offset:56320
	global_load_lds_dwordx4 v[178:179], off
	s_add_i32 m0, s8, 0x2000
	s_add_u32 s8, s40, 0x60080
	v_lshl_add_u64 v[178:179], v[210:211], 0, s[34:35]
	s_addc_u32 s9, s41, 0
	s_add_i32 s40, s66, s68
	global_load_lds_dwordx4 v[178:179], off
	v_lshl_add_u64 v[178:179], s[8:9], 0, v[184:185]
	s_mov_b32 m0, s40
	s_nop 0
	global_load_lds_dwordx4 v[178:179], off
	v_lshl_add_u64 v[178:179], s[8:9], 0, v[188:189]
	s_add_i32 m0, s40, 0x2000
	s_nop 0
	global_load_lds_dwordx4 v[178:179], off
	v_lshl_add_u64 v[178:179], v[212:213], 0, s[34:35]
	s_mov_b32 m0, s81
	s_nop 0
	global_load_lds_dwordx4 v[178:179], off
	v_lshl_add_u64 v[178:179], v[220:221], 0, s[34:35]
	s_mov_b32 m0, s82
	s_nop 0
	global_load_lds_dwordx4 v[178:179], off
	s_waitcnt vmcnt(8)
	s_waitcnt lgkmcnt(0)
	s_barrier
	s_setprio 1
	v_mfma_f32_16x16x32_bf16 v[60:63], v[88:91], v[160:163], v[60:63]
	v_mfma_f32_16x16x32_bf16 v[56:59], v[104:107], v[160:163], v[56:59]
	v_mfma_f32_16x16x32_bf16 v[44:47], v[88:91], v[168:171], v[44:47]
	v_mfma_f32_16x16x32_bf16 v[40:43], v[104:107], v[168:171], v[40:43]
	v_mfma_f32_16x16x32_bf16 v[28:31], v[88:91], v[194:197], v[28:31]
	v_mfma_f32_16x16x32_bf16 v[24:27], v[104:107], v[194:197], v[24:27]
	v_mfma_f32_16x16x32_bf16 v[12:15], v[88:91], v[202:205], v[12:15]
	v_mfma_f32_16x16x32_bf16 v[8:11], v[104:107], v[202:205], v[8:11]
	v_mfma_f32_16x16x32_bf16 v[60:63], v[92:95], v[164:167], v[60:63]
	v_mfma_f32_16x16x32_bf16 v[56:59], v[108:111], v[164:167], v[56:59]
	v_mfma_f32_16x16x32_bf16 v[44:47], v[92:95], v[172:175], v[44:47]
	v_mfma_f32_16x16x32_bf16 v[40:43], v[108:111], v[172:175], v[40:43]
	v_mfma_f32_16x16x32_bf16 v[28:31], v[92:95], v[198:201], v[28:31]
	v_mfma_f32_16x16x32_bf16 v[24:27], v[108:111], v[198:201], v[24:27]
	v_mfma_f32_16x16x32_bf16 v[12:15], v[92:95], v[206:209], v[12:15]
	v_mfma_f32_16x16x32_bf16 v[8:11], v[108:111], v[206:209], v[8:11]
	v_mfma_f32_16x16x32_bf16 v[52:55], v[144:147], v[160:163], v[52:55]
	v_mfma_f32_16x16x32_bf16 v[48:51], v[152:155], v[160:163], v[48:51]
	v_mfma_f32_16x16x32_bf16 v[36:39], v[144:147], v[168:171], v[36:39]
	v_mfma_f32_16x16x32_bf16 v[32:35], v[152:155], v[168:171], v[32:35]
	v_mfma_f32_16x16x32_bf16 v[20:23], v[144:147], v[194:197], v[20:23]
	v_mfma_f32_16x16x32_bf16 v[16:19], v[152:155], v[194:197], v[16:19]
	v_mfma_f32_16x16x32_bf16 v[4:7], v[144:147], v[202:205], v[4:7]
	v_mfma_f32_16x16x32_bf16 v[0:3], v[152:155], v[202:205], v[0:3]
	v_mfma_f32_16x16x32_bf16 v[52:55], v[148:151], v[164:167], v[52:55]
	v_mfma_f32_16x16x32_bf16 v[48:51], v[156:159], v[164:167], v[48:51]
	v_mfma_f32_16x16x32_bf16 v[36:39], v[148:151], v[172:175], v[36:39]
	v_mfma_f32_16x16x32_bf16 v[32:35], v[156:159], v[172:175], v[32:35]
	s_setprio 2
	s_barrier
	v_mfma_f32_16x16x32_bf16 v[20:23], v[148:151], v[198:201], v[20:23]
	v_mfma_f32_16x16x32_bf16 v[16:19], v[156:159], v[198:201], v[16:19]
	v_mfma_f32_16x16x32_bf16 v[4:7], v[148:151], v[206:209], v[4:7]
	v_mfma_f32_16x16x32_bf16 v[0:3], v[156:159], v[206:209], v[0:3]
	s_setprio 0
	s_add_u32 s93, s93, 0x180
	s_addc_u32 s94, s94, 0
	s_cmp_ge_i32 s64, s63
	s_mov_b64 s[8:9], s[38:39]
	s_mov_b32 s40, s64
	s_cbranch_scc1 .Lpeel_exit_5

.LBB0_1220:
	s_ashr_i32 s21, s20, 31
	s_lshl_b64 s[28:29], s[20:21], 19
	s_add_u32 s21, s54, s28
	s_addc_u32 s23, s55, s29
	s_ashr_i32 s27, s26, 31
	s_lshl_b64 s[38:39], s[26:27], 7
	s_add_u32 s28, s21, s38
	s_addc_u32 s29, s23, s39
	s_ashr_i32 s23, s22, 31
	s_lshl_b64 s[50:51], s[22:23], 19
	s_add_u32 s21, s58, s50
	s_addc_u32 s23, s59, s51
	s_add_u32 s38, s21, s38
	s_addc_u32 s39, s23, s39
	s_cmp_lt_i32 s52, 1
	s_cbranch_scc1 .LBB0_1227
	s_and_b64 s[50:51], s[24:25], exec
	s_cselect_b32 s21, s29, s43
	s_cselect_b32 s23, s28, s42
	s_cselect_b32 s27, s39, s5
	s_cselect_b32 s53, s38, s4
	s_add_i32 s63, s52, -2
	s_add_u32 s95, s4, 0x100
	s_addc_u32 vcc_lo, s5, 0
	s_add_u32 s4, s42, 0x40080
	s_addc_u32 s5, s43, 0
	s_mov_b32 s42, 0
	s_add_i32 vcc_hi, s42, 2
	s_add_u32 s43, s4, 0xfffc0080
	s_addc_u32 s50, s5, -1
	s_add_i32 s64, 0, 0x10000
	s_cmp_eq_u32 s63, s42
	s_cselect_b32 s51, s21, s50
	s_cselect_b32 s50, s23, s43
	s_cselect_b32 s43, s27, vcc_lo
	s_cselect_b32 s42, s53, s95
	s_add_i32 s66, 0, 0x14000
	v_add_u32_e32 v108, s64, v228
	v_add_u32_e32 v156, s66, v228
	ds_read_b128 v[88:91], v108
	ds_read_b128 v[92:95], v108 offset:1024
	ds_read_b128 v[104:107], v108 offset:2048
	ds_read_b128 v[108:111], v108 offset:3072
	ds_read_b128 v[144:147], v156
	ds_read_b128 v[148:151], v156 offset:1024
	ds_read_b128 v[152:155], v156 offset:2048
	ds_read_b128 v[156:159], v156 offset:3072
	v_lshl_add_u64 v[178:179], s[4:5], 0, v[192:193]
	s_add_i32 m0, s7, 0xc000
	ds_read_b128 v[160:163], v232
	ds_read_b128 v[164:167], v232 offset:1024
	ds_read_b128 v[168:171], v232 offset:2048
	ds_read_b128 v[172:175], v232 offset:3072
	ds_read_b128 v[194:197], v232 offset:4096
	ds_read_b128 v[198:201], v232 offset:5120
	ds_read_b128 v[202:205], v232 offset:6144
	ds_read_b128 v[206:209], v232 offset:7168
	global_load_lds_dwordx4 v[178:179], off
	v_lshl_add_u64 v[178:179], s[4:5], 0, v[190:191]
	s_add_i32 m0, s7, 0xe000
	s_nop 0
	global_load_lds_dwordx4 v[178:179], off
	s_waitcnt vmcnt(24)
	s_waitcnt lgkmcnt(0)
	s_barrier
	s_setprio 1
	v_mfma_f32_16x16x32_bf16 v[140:143], v[88:91], v[160:163], 0
	v_mfma_f32_16x16x32_bf16 v[136:139], v[104:107], v[160:163], 0
	v_mfma_f32_16x16x32_bf16 v[124:127], v[88:91], v[168:171], 0
	v_mfma_f32_16x16x32_bf16 v[120:123], v[104:107], v[168:171], 0
	v_mfma_f32_16x16x32_bf16 v[100:103], v[88:91], v[194:197], 0
	v_mfma_f32_16x16x32_bf16 v[96:99], v[104:107], v[194:197], 0
	v_mfma_f32_16x16x32_bf16 v[76:79], v[88:91], v[202:205], 0
	v_mfma_f32_16x16x32_bf16 v[72:75], v[104:107], v[202:205], 0
	v_mfma_f32_16x16x32_bf16 v[140:143], v[92:95], v[164:167], v[140:143]
	v_mfma_f32_16x16x32_bf16 v[136:139], v[108:111], v[164:167], v[136:139]
	v_mfma_f32_16x16x32_bf16 v[124:127], v[92:95], v[172:175], v[124:127]
	v_mfma_f32_16x16x32_bf16 v[120:123], v[108:111], v[172:175], v[120:123]
	v_mfma_f32_16x16x32_bf16 v[100:103], v[92:95], v[198:201], v[100:103]
	v_mfma_f32_16x16x32_bf16 v[96:99], v[108:111], v[198:201], v[96:99]
	v_mfma_f32_16x16x32_bf16 v[76:79], v[92:95], v[206:209], v[76:79]
	v_mfma_f32_16x16x32_bf16 v[72:75], v[108:111], v[206:209], v[72:75]
	v_mfma_f32_16x16x32_bf16 v[132:135], v[144:147], v[160:163], 0
	v_mfma_f32_16x16x32_bf16 v[128:131], v[152:155], v[160:163], 0
	v_mfma_f32_16x16x32_bf16 v[116:119], v[144:147], v[168:171], 0
	v_mfma_f32_16x16x32_bf16 v[112:115], v[152:155], v[168:171], 0
	v_mfma_f32_16x16x32_bf16 v[84:87], v[144:147], v[194:197], 0
	v_mfma_f32_16x16x32_bf16 v[80:83], v[152:155], v[194:197], 0
	v_mfma_f32_16x16x32_bf16 v[68:71], v[144:147], v[202:205], 0
	v_mfma_f32_16x16x32_bf16 v[64:67], v[152:155], v[202:205], 0
	v_mfma_f32_16x16x32_bf16 v[132:135], v[148:151], v[164:167], v[132:135]
	v_mfma_f32_16x16x32_bf16 v[128:131], v[156:159], v[164:167], v[128:131]
	v_mfma_f32_16x16x32_bf16 v[116:119], v[148:151], v[172:175], v[116:119]
	v_mfma_f32_16x16x32_bf16 v[112:115], v[156:159], v[172:175], v[112:115]
	s_setprio 2
	s_barrier
	v_mfma_f32_16x16x32_bf16 v[84:87], v[148:151], v[198:201], v[84:87]
	v_mfma_f32_16x16x32_bf16 v[80:83], v[156:159], v[198:201], v[80:83]
	v_mfma_f32_16x16x32_bf16 v[68:71], v[148:151], v[206:209], v[68:71]
	v_mfma_f32_16x16x32_bf16 v[64:67], v[156:159], v[206:209], v[64:67]
	s_setprio 0
	s_add_i32 s64, s64, s72
	v_lshl_add_u64 v[178:179], s[42:43], 0, v[184:185]
	s_mov_b32 m0, s64
	ds_read_b128 v[160:163], v232 offset:16384
	ds_read_b128 v[164:167], v232 offset:17408
	ds_read_b128 v[168:171], v232 offset:18432
	ds_read_b128 v[172:175], v232 offset:19456
	ds_read_b128 v[194:197], v232 offset:20480
	ds_read_b128 v[198:201], v232 offset:21504
	ds_read_b128 v[202:205], v232 offset:22528
	ds_read_b128 v[206:209], v232 offset:23552
	global_load_lds_dwordx4 v[178:179], off
	s_add_i32 m0, s64, 0x2000
	s_add_u32 s64, s42, 0x40000
	v_lshl_add_u64 v[210:211], s[42:43], 0, v[188:189]
	s_addc_u32 s65, s43, 0
	s_add_i32 s66, s66, s72
	global_load_lds_dwordx4 v[210:211], off
	v_lshl_add_u64 v[212:213], s[64:65], 0, v[184:185]
	s_mov_b32 m0, s66
	v_lshl_add_u64 v[220:221], s[50:51], 0, v[186:187]
	global_load_lds_dwordx4 v[212:213], off
	v_lshl_add_u64 v[212:213], s[64:65], 0, v[188:189]
	s_add_i32 m0, s66, 0x2000
	s_nop 0
	global_load_lds_dwordx4 v[212:213], off
	v_lshl_add_u64 v[212:213], s[50:51], 0, v[182:183]
	s_mov_b32 m0, s7
	s_nop 0
	global_load_lds_dwordx4 v[212:213], off
	s_mov_b32 m0, s73
	s_nop 0
	global_load_lds_dwordx4 v[220:221], off
	s_waitcnt vmcnt(8)
	s_waitcnt lgkmcnt(0)
	s_barrier
	s_setprio 1
	v_mfma_f32_16x16x32_bf16 v[60:63], v[88:91], v[160:163], 0
	v_mfma_f32_16x16x32_bf16 v[56:59], v[104:107], v[160:163], 0
	v_mfma_f32_16x16x32_bf16 v[44:47], v[88:91], v[168:171], 0
	v_mfma_f32_16x16x32_bf16 v[40:43], v[104:107], v[168:171], 0
	v_mfma_f32_16x16x32_bf16 v[28:31], v[88:91], v[194:197], 0
	v_mfma_f32_16x16x32_bf16 v[24:27], v[104:107], v[194:197], 0
	v_mfma_f32_16x16x32_bf16 v[12:15], v[88:91], v[202:205], 0
	v_mfma_f32_16x16x32_bf16 v[8:11], v[104:107], v[202:205], 0
	v_mfma_f32_16x16x32_bf16 v[60:63], v[92:95], v[164:167], v[60:63]
	v_mfma_f32_16x16x32_bf16 v[56:59], v[108:111], v[164:167], v[56:59]
	v_mfma_f32_16x16x32_bf16 v[44:47], v[92:95], v[172:175], v[44:47]
	v_mfma_f32_16x16x32_bf16 v[40:43], v[108:111], v[172:175], v[40:43]
	v_mfma_f32_16x16x32_bf16 v[28:31], v[92:95], v[198:201], v[28:31]
	v_mfma_f32_16x16x32_bf16 v[24:27], v[108:111], v[198:201], v[24:27]
	v_mfma_f32_16x16x32_bf16 v[12:15], v[92:95], v[206:209], v[12:15]
	v_mfma_f32_16x16x32_bf16 v[8:11], v[108:111], v[206:209], v[8:11]
	v_mfma_f32_16x16x32_bf16 v[52:55], v[144:147], v[160:163], 0
	v_mfma_f32_16x16x32_bf16 v[48:51], v[152:155], v[160:163], 0
	v_mfma_f32_16x16x32_bf16 v[36:39], v[144:147], v[168:171], 0
	v_mfma_f32_16x16x32_bf16 v[32:35], v[152:155], v[168:171], 0
	v_mfma_f32_16x16x32_bf16 v[20:23], v[144:147], v[194:197], 0
	v_mfma_f32_16x16x32_bf16 v[16:19], v[152:155], v[194:197], 0
	v_mfma_f32_16x16x32_bf16 v[4:7], v[144:147], v[202:205], 0
	v_mfma_f32_16x16x32_bf16 v[0:3], v[152:155], v[202:205], 0
	v_mfma_f32_16x16x32_bf16 v[52:55], v[148:151], v[164:167], v[52:55]
	v_mfma_f32_16x16x32_bf16 v[48:51], v[156:159], v[164:167], v[48:51]
	v_mfma_f32_16x16x32_bf16 v[36:39], v[148:151], v[172:175], v[36:39]
	v_mfma_f32_16x16x32_bf16 v[32:35], v[156:159], v[172:175], v[32:35]
	s_setprio 2
	s_barrier
	v_mfma_f32_16x16x32_bf16 v[20:23], v[148:151], v[198:201], v[20:23]
	v_mfma_f32_16x16x32_bf16 v[16:19], v[156:159], v[198:201], v[16:19]
	v_mfma_f32_16x16x32_bf16 v[4:7], v[148:151], v[206:209], v[4:7]
	v_mfma_f32_16x16x32_bf16 v[0:3], v[156:159], v[206:209], v[0:3]
	s_setprio 0
	s_add_i32 s64, 0, 0x18000
	s_add_i32 s65, 0, 0x1c000
	v_add_u32_e32 v108, s64, v228
	v_add_u32_e32 v156, s65, v228
	ds_read_b128 v[88:91], v108
	ds_read_b128 v[92:95], v108 offset:1024
	ds_read_b128 v[104:107], v108 offset:2048
	ds_read_b128 v[108:111], v108 offset:3072
	ds_read_b128 v[144:147], v156
	ds_read_b128 v[148:151], v156 offset:1024
	ds_read_b128 v[152:155], v156 offset:2048
	ds_read_b128 v[156:159], v156 offset:3072
	s_add_u32 s50, s50, 0x40000
	s_addc_u32 s51, s51, 0
	s_mov_b32 m0, s74
	v_lshl_add_u64 v[222:223], s[50:51], 0, v[182:183]
	ds_read_b128 v[160:163], v232 offset:32768
	ds_read_b128 v[164:167], v232 offset:33792
	ds_read_b128 v[168:171], v232 offset:34816
	ds_read_b128 v[172:175], v232 offset:35840
	ds_read_b128 v[194:197], v232 offset:36864
	ds_read_b128 v[198:201], v232 offset:37888
	ds_read_b128 v[202:205], v232 offset:38912
	ds_read_b128 v[206:209], v232 offset:39936
	global_load_lds_dwordx4 v[222:223], off
	v_lshl_add_u64 v[222:223], s[50:51], 0, v[186:187]
	s_mov_b32 m0, s75
	s_nop 0
	global_load_lds_dwordx4 v[222:223], off
	s_waitcnt vmcnt(8)
	s_waitcnt lgkmcnt(0)
	s_barrier
	s_setprio 1
	v_mfma_f32_16x16x32_bf16 v[140:143], v[88:91], v[160:163], v[140:143]
	v_mfma_f32_16x16x32_bf16 v[136:139], v[104:107], v[160:163], v[136:139]
	v_mfma_f32_16x16x32_bf16 v[124:127], v[88:91], v[168:171], v[124:127]
	v_mfma_f32_16x16x32_bf16 v[120:123], v[104:107], v[168:171], v[120:123]
	v_mfma_f32_16x16x32_bf16 v[100:103], v[88:91], v[194:197], v[100:103]
	v_mfma_f32_16x16x32_bf16 v[96:99], v[104:107], v[194:197], v[96:99]
	v_mfma_f32_16x16x32_bf16 v[76:79], v[88:91], v[202:205], v[76:79]
	v_mfma_f32_16x16x32_bf16 v[72:75], v[104:107], v[202:205], v[72:75]
	v_mfma_f32_16x16x32_bf16 v[140:143], v[92:95], v[164:167], v[140:143]
	v_mfma_f32_16x16x32_bf16 v[136:139], v[108:111], v[164:167], v[136:139]
	v_mfma_f32_16x16x32_bf16 v[124:127], v[92:95], v[172:175], v[124:127]
	v_mfma_f32_16x16x32_bf16 v[120:123], v[108:111], v[172:175], v[120:123]
	v_mfma_f32_16x16x32_bf16 v[100:103], v[92:95], v[198:201], v[100:103]
	v_mfma_f32_16x16x32_bf16 v[96:99], v[108:111], v[198:201], v[96:99]
	v_mfma_f32_16x16x32_bf16 v[76:79], v[92:95], v[206:209], v[76:79]
	v_mfma_f32_16x16x32_bf16 v[72:75], v[108:111], v[206:209], v[72:75]
	v_mfma_f32_16x16x32_bf16 v[132:135], v[144:147], v[160:163], v[132:135]
	v_mfma_f32_16x16x32_bf16 v[128:131], v[152:155], v[160:163], v[128:131]
	v_mfma_f32_16x16x32_bf16 v[116:119], v[144:147], v[168:171], v[116:119]
	v_mfma_f32_16x16x32_bf16 v[112:115], v[152:155], v[168:171], v[112:115]
	v_mfma_f32_16x16x32_bf16 v[84:87], v[144:147], v[194:197], v[84:87]
	v_mfma_f32_16x16x32_bf16 v[80:83], v[152:155], v[194:197], v[80:83]
	v_mfma_f32_16x16x32_bf16 v[68:71], v[144:147], v[202:205], v[68:71]
	v_mfma_f32_16x16x32_bf16 v[64:67], v[152:155], v[202:205], v[64:67]
	v_mfma_f32_16x16x32_bf16 v[132:135], v[148:151], v[164:167], v[132:135]
	v_mfma_f32_16x16x32_bf16 v[128:131], v[156:159], v[164:167], v[128:131]
	v_mfma_f32_16x16x32_bf16 v[116:119], v[148:151], v[172:175], v[116:119]
	v_mfma_f32_16x16x32_bf16 v[112:115], v[156:159], v[172:175], v[112:115]
	s_setprio 2
	s_barrier
	v_mfma_f32_16x16x32_bf16 v[84:87], v[148:151], v[198:201], v[84:87]
	v_mfma_f32_16x16x32_bf16 v[80:83], v[156:159], v[198:201], v[80:83]
	v_mfma_f32_16x16x32_bf16 v[68:71], v[148:151], v[206:209], v[68:71]
	v_mfma_f32_16x16x32_bf16 v[64:67], v[156:159], v[206:209], v[64:67]
	s_setprio 0
	s_add_i32 s50, s64, s72
	v_lshl_add_u64 v[178:179], v[178:179], 0, s[34:35]
	s_mov_b32 m0, s50
	ds_read_b128 v[160:163], v232 offset:49152
	ds_read_b128 v[164:167], v232 offset:50176
	ds_read_b128 v[168:171], v232 offset:51200
	ds_read_b128 v[172:175], v232 offset:52224
	ds_read_b128 v[194:197], v232 offset:53248
	ds_read_b128 v[198:201], v232 offset:54272
	ds_read_b128 v[202:205], v232 offset:55296
	ds_read_b128 v[206:209], v232 offset:56320
	global_load_lds_dwordx4 v[178:179], off
	s_add_i32 m0, s50, 0x2000
	s_add_u32 s42, s42, 0x40080
	v_lshl_add_u64 v[178:179], v[210:211], 0, s[34:35]
	s_addc_u32 s43, s43, 0
	s_add_i32 s50, s65, s72
	global_load_lds_dwordx4 v[178:179], off
	v_lshl_add_u64 v[178:179], s[42:43], 0, v[184:185]
	s_mov_b32 m0, s50
	s_nop 0
	global_load_lds_dwordx4 v[178:179], off
	v_lshl_add_u64 v[178:179], s[42:43], 0, v[188:189]
	s_add_i32 m0, s50, 0x2000
	s_nop 0
	global_load_lds_dwordx4 v[178:179], off
	v_lshl_add_u64 v[178:179], v[212:213], 0, s[34:35]
	s_mov_b32 m0, s81
	s_nop 0
	global_load_lds_dwordx4 v[178:179], off
	v_lshl_add_u64 v[178:179], v[220:221], 0, s[34:35]
	s_mov_b32 m0, s82
	s_nop 0
	global_load_lds_dwordx4 v[178:179], off
	s_waitcnt vmcnt(8)
	s_waitcnt lgkmcnt(0)
	s_barrier
	s_setprio 1
	v_mfma_f32_16x16x32_bf16 v[60:63], v[88:91], v[160:163], v[60:63]
	v_mfma_f32_16x16x32_bf16 v[56:59], v[104:107], v[160:163], v[56:59]
	v_mfma_f32_16x16x32_bf16 v[44:47], v[88:91], v[168:171], v[44:47]
	v_mfma_f32_16x16x32_bf16 v[40:43], v[104:107], v[168:171], v[40:43]
	v_mfma_f32_16x16x32_bf16 v[28:31], v[88:91], v[194:197], v[28:31]
	v_mfma_f32_16x16x32_bf16 v[24:27], v[104:107], v[194:197], v[24:27]
	v_mfma_f32_16x16x32_bf16 v[12:15], v[88:91], v[202:205], v[12:15]
	v_mfma_f32_16x16x32_bf16 v[8:11], v[104:107], v[202:205], v[8:11]
	v_mfma_f32_16x16x32_bf16 v[60:63], v[92:95], v[164:167], v[60:63]
	v_mfma_f32_16x16x32_bf16 v[56:59], v[108:111], v[164:167], v[56:59]
	v_mfma_f32_16x16x32_bf16 v[44:47], v[92:95], v[172:175], v[44:47]
	v_mfma_f32_16x16x32_bf16 v[40:43], v[108:111], v[172:175], v[40:43]
	v_mfma_f32_16x16x32_bf16 v[28:31], v[92:95], v[198:201], v[28:31]
	v_mfma_f32_16x16x32_bf16 v[24:27], v[108:111], v[198:201], v[24:27]
	v_mfma_f32_16x16x32_bf16 v[12:15], v[92:95], v[206:209], v[12:15]
	v_mfma_f32_16x16x32_bf16 v[8:11], v[108:111], v[206:209], v[8:11]
	v_mfma_f32_16x16x32_bf16 v[52:55], v[144:147], v[160:163], v[52:55]
	v_mfma_f32_16x16x32_bf16 v[48:51], v[152:155], v[160:163], v[48:51]
	v_mfma_f32_16x16x32_bf16 v[36:39], v[144:147], v[168:171], v[36:39]
	v_mfma_f32_16x16x32_bf16 v[32:35], v[152:155], v[168:171], v[32:35]
	v_mfma_f32_16x16x32_bf16 v[20:23], v[144:147], v[194:197], v[20:23]
	v_mfma_f32_16x16x32_bf16 v[16:19], v[152:155], v[194:197], v[16:19]
	v_mfma_f32_16x16x32_bf16 v[4:7], v[144:147], v[202:205], v[4:7]
	v_mfma_f32_16x16x32_bf16 v[0:3], v[152:155], v[202:205], v[0:3]
	v_mfma_f32_16x16x32_bf16 v[52:55], v[148:151], v[164:167], v[52:55]
	v_mfma_f32_16x16x32_bf16 v[48:51], v[156:159], v[164:167], v[48:51]
	v_mfma_f32_16x16x32_bf16 v[36:39], v[148:151], v[172:175], v[36:39]
	v_mfma_f32_16x16x32_bf16 v[32:35], v[156:159], v[172:175], v[32:35]
	s_setprio 2
	s_barrier
	v_mfma_f32_16x16x32_bf16 v[20:23], v[148:151], v[198:201], v[20:23]
	v_mfma_f32_16x16x32_bf16 v[16:19], v[156:159], v[198:201], v[16:19]
	v_mfma_f32_16x16x32_bf16 v[4:7], v[148:151], v[206:209], v[4:7]
	v_mfma_f32_16x16x32_bf16 v[0:3], v[156:159], v[206:209], v[0:3]
	s_setprio 0
	s_add_u32 s95, s95, 0x100
	s_addc_u32 vcc_lo, vcc_lo, 0
	s_add_u32 s4, s4, 0x100
	s_addc_u32 s5, s5, 0
	s_cmp_ge_i32 vcc_hi, s52
	s_mov_b32 s42, vcc_hi
	s_cbranch_scc1 .Lpeel_exit_6
